# stack + GEMM k-loop nop removal after SGPR-base loads + NSA fast-path addend select and ballot hoisted before the barrier
# speedup vs baseline: 1.0063x; 1.0020x over previous
; DI f32x4 mfma16(bf16x8 a, bf16x8 b, f32x4 c) { return __builtin_amdgcn_mfma_f32_16x16x32_bf16(a, b, c, 0, 0, 0); }
; #pragma unroll
;   for (int ks = KS0; ks < KS1; ++ks) {
;     bf16x8 af[8], bfr[4];
; #pragma unroll
;     for (int i = 0; i < 8; ++i) {
;       const int r = wm * 128 + i * 16 + (lane & 15);
;       af[i] = *(const bf16x8*)(S + r * 64 + (((ks * 4 + (lane >> 4)) ^ ((r >> 1) & 7)) << 3));
;     }
; #pragma unroll
;     for (int j = 0; j < 4; ++j) {
;       const int r = wn * 64 + j * 16 + (lane & 15);
;       bfr[j] = *(const bf16x8*)(S + 16384 + r * 64 + (((ks * 4 + (lane >> 4)) ^ ((r >> 1) & 7)) << 3));
;     }
;     __builtin_amdgcn_s_setprio(1);
; #pragma unroll
;     for (int i = 0; i < 8; ++i)
; #pragma unroll
;       for (int j = 0; j < 4; ++j) acc[i][j] = mfma16(bfr[j], af[i], acc[i][j]);
;     __builtin_amdgcn_s_setprio(0);
;   }
; }
; DI void gemm8_accum(f32x4 (&acc)[8][4], const bf16_t* a, size_t lda, const bf16_t* b, size_t ldb, int nkb, bf16_t* L,
;                     const bool pre, const bf16_t* an, size_t ldan, const bf16_t* bn, size_t ldbn) {
;     ...
;   for (int kb = 0; kb + 2 < nkb; ++kb) {
;     __syncthreads();
;     g8_store1(L + ((kb + 1) & 1) * 32768, ra, lrow, lch);
;     g8_load1o(ra, a + (kb + 2) * 64, offa);
;     __builtin_amdgcn_sched_barrier(0);
;     g8_compute<0, 1>(acc, L + (kb & 1) * 32768, wm, wn, lane);
;     __builtin_amdgcn_sched_barrier(0);
;     g8_store1(L + ((kb + 1) & 1) * 32768 + 16384, rb, lrow, lch);
;     g8_load1o(rb, b + (kb + 2) * 64, offb);
;     __builtin_amdgcn_sched_barrier(0);
;     g8_compute<1, 2>(acc, L + (kb & 1) * 32768, wm, wn, lane);
;   }
.Lstg_134_a:
	s_waitcnt vmcnt(5)
	ds_write_b128 v167, v[22:25]
	ds_write_b128 v167, v[18:21] offset:8192
	ds_write_b128 v167, v[26:29] offset:16384
	s_waitcnt vmcnt(4)
	ds_write_b128 v167, v[30:33] offset:24576
	s_add_u32 s54, s52, s0
	s_addc_u32 s55, s53, s1
	global_load_dwordx4 v[22:25], v185, s[54:55]
	global_load_dwordx4 v[26:29], v181, s[54:55]
	global_load_dwordx4 v[18:21], v183, s[54:55]
	global_load_dwordx4 v[30:33], v179, s[54:55]
	s_and_b32 s2, s2, 0x8000
	s_lshl_b32 s2, s2, 1
	v_lshl_add_u32 v169, v191, 1, s2
	v_add_u32_e32 v198, v169, v187
	ds_read_b128 v[192:195], v198
	ds_read_b128 v[206:209], v198 offset:2048
	ds_read_b128 v[210:213], v198 offset:4096
	ds_read_b128 v[214:217], v198 offset:6144
	ds_read_b128 v[218:221], v198 offset:8192
	ds_read_b128 v[222:225], v198 offset:10240
	ds_read_b128 v[226:229], v198 offset:12288
	ds_read_b128 v[230:233], v198 offset:14336
	v_add_u32_e32 v169, v169, v186
	ds_read_b128 v[234:237], v169 offset:32768
	ds_read_b128 v[238:241], v169 offset:34816
	ds_read_b128 v[242:245], v169 offset:36864
	ds_read_b128 v[246:249], v169 offset:38912
	s_waitcnt lgkmcnt(3)
	v_mfma_f32_16x16x32_bf16 v[34:37], v[234:237], v[192:195], v[34:37]
	s_waitcnt lgkmcnt(2)
	v_mfma_f32_16x16x32_bf16 v[38:41], v[238:241], v[192:195], v[38:41]
	s_waitcnt lgkmcnt(1)
	v_mfma_f32_16x16x32_bf16 v[42:45], v[242:245], v[192:195], v[42:45]
	s_waitcnt lgkmcnt(0)
	v_mfma_f32_16x16x32_bf16 v[46:49], v[246:249], v[192:195], v[46:49]
	v_mfma_f32_16x16x32_bf16 v[50:53], v[234:237], v[206:209], v[50:53]
	v_mfma_f32_16x16x32_bf16 v[54:57], v[238:241], v[206:209], v[54:57]
	v_mfma_f32_16x16x32_bf16 v[58:61], v[242:245], v[206:209], v[58:61]
	v_mfma_f32_16x16x32_bf16 v[62:65], v[246:249], v[206:209], v[62:65]
	v_mfma_f32_16x16x32_bf16 v[66:69], v[234:237], v[210:213], v[66:69]
	v_mfma_f32_16x16x32_bf16 v[70:73], v[238:241], v[210:213], v[70:73]
	v_mfma_f32_16x16x32_bf16 v[74:77], v[242:245], v[210:213], v[74:77]
	v_mfma_f32_16x16x32_bf16 v[78:81], v[246:249], v[210:213], v[78:81]
	v_mfma_f32_16x16x32_bf16 v[82:85], v[234:237], v[214:217], v[82:85]
	v_mfma_f32_16x16x32_bf16 v[86:89], v[238:241], v[214:217], v[86:89]
	v_mfma_f32_16x16x32_bf16 v[90:93], v[242:245], v[214:217], v[90:93]
	v_mfma_f32_16x16x32_bf16 v[94:97], v[246:249], v[214:217], v[94:97]
	v_mfma_f32_16x16x32_bf16 v[98:101], v[234:237], v[218:221], v[98:101]
	v_mfma_f32_16x16x32_bf16 v[102:105], v[238:241], v[218:221], v[102:105]
	v_mfma_f32_16x16x32_bf16 v[106:109], v[242:245], v[218:221], v[106:109]
	v_mfma_f32_16x16x32_bf16 v[110:113], v[246:249], v[218:221], v[110:113]
	v_mfma_f32_16x16x32_bf16 v[114:117], v[234:237], v[222:225], v[114:117]
	v_mfma_f32_16x16x32_bf16 v[118:121], v[238:241], v[222:225], v[118:121]
	v_mfma_f32_16x16x32_bf16 v[122:125], v[242:245], v[222:225], v[122:125]
	v_mfma_f32_16x16x32_bf16 v[126:129], v[246:249], v[222:225], v[126:129]
	v_mfma_f32_16x16x32_bf16 v[130:133], v[234:237], v[226:229], v[130:133]
	v_mfma_f32_16x16x32_bf16 v[134:137], v[238:241], v[226:229], v[134:137]
	v_mfma_f32_16x16x32_bf16 v[138:141], v[242:245], v[226:229], v[138:141]
	v_mfma_f32_16x16x32_bf16 v[142:145], v[246:249], v[226:229], v[142:145]
	v_mfma_f32_16x16x32_bf16 v[146:149], v[234:237], v[230:233], v[146:149]
	v_mfma_f32_16x16x32_bf16 v[150:153], v[238:241], v[230:233], v[150:153]
	v_mfma_f32_16x16x32_bf16 v[154:157], v[242:245], v[230:233], v[154:157]
	v_mfma_f32_16x16x32_bf16 v[158:161], v[246:249], v[230:233], v[158:161]
	s_waitcnt vmcnt(7)
	ds_write_b128 v167, v[6:9] offset:32768
	s_waitcnt vmcnt(6)
	ds_write_b128 v167, v[2:5] offset:40960
	s_waitcnt vmcnt(5)
	ds_write_b128 v167, v[10:13] offset:49152
	s_waitcnt vmcnt(4)
	ds_write_b128 v167, v[14:17] offset:57344
	s_add_u32 s58, s56, s0
	s_addc_u32 s59, s57, s1
	global_load_dwordx4 v[6:9], v177, s[58:59]
	global_load_dwordx4 v[2:5], v175, s[58:59]
	global_load_dwordx4 v[10:13], v173, s[58:59]
	global_load_dwordx4 v[14:17], v171, s[58:59]
	v_lshl_add_u32 v167, v188, 1, s2
	v_add_u32_e32 v169, v167, v187
	ds_read_b128 v[192:195], v169
	ds_read_b128 v[206:209], v169 offset:2048
	ds_read_b128 v[210:213], v169 offset:4096
	ds_read_b128 v[214:217], v169 offset:6144
	ds_read_b128 v[218:221], v169 offset:8192
	ds_read_b128 v[222:225], v169 offset:10240
	ds_read_b128 v[226:229], v169 offset:12288
	ds_read_b128 v[230:233], v169 offset:14336
	v_add_u32_e32 v167, v167, v186
	ds_read_b128 v[234:237], v167 offset:32768
	ds_read_b128 v[238:241], v167 offset:34816
	ds_read_b128 v[242:245], v167 offset:36864
	ds_read_b128 v[246:249], v167 offset:38912
	s_cmp_lg_u32 s101, 0
	s_cbranch_scc1 .Lstg_134_b
	s_waitcnt lgkmcnt(3)
	v_mfma_f32_16x16x32_bf16 v[34:37], v[234:237], v[192:195], v[34:37]
	s_waitcnt lgkmcnt(2)
	v_mfma_f32_16x16x32_bf16 v[38:41], v[238:241], v[192:195], v[38:41]
	s_waitcnt lgkmcnt(1)
	v_mfma_f32_16x16x32_bf16 v[42:45], v[242:245], v[192:195], v[42:45]
	s_waitcnt lgkmcnt(0)
	v_mfma_f32_16x16x32_bf16 v[46:49], v[246:249], v[192:195], v[46:49]
	v_mfma_f32_16x16x32_bf16 v[50:53], v[234:237], v[206:209], v[50:53]
	v_mfma_f32_16x16x32_bf16 v[54:57], v[238:241], v[206:209], v[54:57]
	v_mfma_f32_16x16x32_bf16 v[58:61], v[242:245], v[206:209], v[58:61]
	v_mfma_f32_16x16x32_bf16 v[62:65], v[246:249], v[206:209], v[62:65]
	v_mfma_f32_16x16x32_bf16 v[66:69], v[234:237], v[210:213], v[66:69]
	v_mfma_f32_16x16x32_bf16 v[70:73], v[238:241], v[210:213], v[70:73]
	v_mfma_f32_16x16x32_bf16 v[74:77], v[242:245], v[210:213], v[74:77]
	v_mfma_f32_16x16x32_bf16 v[78:81], v[246:249], v[210:213], v[78:81]
	v_mfma_f32_16x16x32_bf16 v[82:85], v[234:237], v[214:217], v[82:85]
	v_mfma_f32_16x16x32_bf16 v[86:89], v[238:241], v[214:217], v[86:89]
	v_mfma_f32_16x16x32_bf16 v[90:93], v[242:245], v[214:217], v[90:93]
	v_mfma_f32_16x16x32_bf16 v[94:97], v[246:249], v[214:217], v[94:97]
	v_mfma_f32_16x16x32_bf16 v[98:101], v[234:237], v[218:221], v[98:101]
	v_mfma_f32_16x16x32_bf16 v[102:105], v[238:241], v[218:221], v[102:105]
	v_mfma_f32_16x16x32_bf16 v[106:109], v[242:245], v[218:221], v[106:109]
	v_mfma_f32_16x16x32_bf16 v[110:113], v[246:249], v[218:221], v[110:113]
	v_mfma_f32_16x16x32_bf16 v[114:117], v[234:237], v[222:225], v[114:117]
	v_mfma_f32_16x16x32_bf16 v[118:121], v[238:241], v[222:225], v[118:121]
	v_mfma_f32_16x16x32_bf16 v[122:125], v[242:245], v[222:225], v[122:125]
	v_mfma_f32_16x16x32_bf16 v[126:129], v[246:249], v[222:225], v[126:129]
	v_mfma_f32_16x16x32_bf16 v[130:133], v[234:237], v[226:229], v[130:133]
	v_mfma_f32_16x16x32_bf16 v[134:137], v[238:241], v[226:229], v[134:137]
	v_mfma_f32_16x16x32_bf16 v[138:141], v[242:245], v[226:229], v[138:141]
	v_mfma_f32_16x16x32_bf16 v[142:145], v[246:249], v[226:229], v[142:145]
	v_mfma_f32_16x16x32_bf16 v[146:149], v[234:237], v[230:233], v[146:149]
	v_mfma_f32_16x16x32_bf16 v[150:153], v[238:241], v[230:233], v[150:153]
	v_mfma_f32_16x16x32_bf16 v[154:157], v[242:245], v[230:233], v[154:157]
	v_mfma_f32_16x16x32_bf16 v[158:161], v[246:249], v[230:233], v[158:161]

; template <int MODE, bool FX>
; DI void attn_compute(const int lane, const bf16_t* Ks, const bf16_t* Vs, const bf16x8 (&qf)[2][2], AttnSt& st, const float (&invl)[2],
;                      int lo, int hi, float (&impA)[4], float (&impE)[4], const float CL) {
;     ...
;   for (int ks = 0; ks < 2; ++ks) {
; #pragma unroll
;     for (int kt = 0; kt < 4; ++kt) {
;       int row = kt * 16 + col;
;       bf16x8 kf = *(const bf16x8*)(Ks + row * 64 + (((ks * 4 + quad) ^ ((row >> 1) & 7)) << 3));
; #pragma unroll
;       for (int hh = 0; hh < 2; ++hh) S[kt][hh] = mfma16(kf, qf[hh][ks], S[kt][hh]);
;     }
;   }
;   bf16x8 pf[2][2];
;   const bool full = (lo <= 0) && (hi >= 63);
;   const bool none = (hi < 0) || (lo > 63) || (hi < lo);
;   if (__all(full || none)) {
;     constexpr float L2E = 1.4426950408889634f;
; #pragma unroll
;     for (int hh = 0; hh < 2; ++hh) {
;       float mL;
;       float il = 1.f;
;       if (FX) {
;         mL = full ? CL : 1e30f;
;         if (MODE == 1) il = invl[hh];
;       } else if (MODE != 1) {
;         float mx = -1e30f;
; #pragma unroll
;         for (int kt = 0; kt < 4; ++kt)
; #pragma unroll
;           for (int j = 0; j < 4; ++j) mx = fmaxf(mx, S[kt][hh][j]);
;         mx = full ? mx : -1e30f;
;         mx = fmaxf(mx, shx(mx, 16, lane));
;         mx = fmaxf(mx, shx(mx, 32, lane));
;         const float m_new = fmaxf(st.m[hh], mx);
;         const float alpha = __expf(st.m[hh] - m_new);
;         st.m[hh] = m_new;
;         st.l[hh] *= alpha;
;         if (MODE == 2) {
; #pragma unroll
;           for (int dt = 0; dt < 4; ++dt) st.O[hh][dt] *= alpha;
;         }
;         mL = full ? m_new * L2E : 1e30f;
;       } else {
;         mL = full ? st.m[hh] * L2E : 1e30f;
;         il = invl[hh];
;       }
;       float rs = 0.f;
; #pragma unroll
;       for (int kt = 0; kt < 4; ++kt) {
;         float a = 0.f;
; #pragma unroll
;         for (int j = 0; j < 4; ++j) {
;           float pv = __builtin_amdgcn_exp2f(fmaf(S[kt][hh][j], L2E, -mL));
;           if (MODE == 1) pv *= il;
;           S[kt][hh][j] = pv;
;           a += pv;
;         }
;     ...
;   if (MODE != 0) {
; #pragma unroll
;     for (int dt = 0; dt < 4; ++dt) {
;       const int row = dt * 16 + col;
;       const int sw = (row >> 1) & 7;
; #pragma unroll
;       for (int c = 0; c < 2; ++c) {
.Lnsa_fast_p1:
	s_waitcnt lgkmcnt(7)
	v_mfma_f32_16x16x32_bf16 v[98:101], v[220:223], v[2:5], 0
	s_waitcnt lgkmcnt(6)
	v_mfma_f32_16x16x32_bf16 v[106:109], v[224:227], v[2:5], 0
	s_waitcnt lgkmcnt(5)
	v_mfma_f32_16x16x32_bf16 v[102:105], v[228:231], v[2:5], 0
	s_waitcnt lgkmcnt(4)
	v_mfma_f32_16x16x32_bf16 v[110:113], v[232:235], v[2:5], 0
	s_waitcnt lgkmcnt(3)
	v_mfma_f32_16x16x32_bf16 v[98:101], v[236:239], v[6:9], v[98:101]
	s_waitcnt lgkmcnt(2)
	v_mfma_f32_16x16x32_bf16 v[106:109], v[240:243], v[6:9], v[106:109]
	s_waitcnt lgkmcnt(1)
	v_mfma_f32_16x16x32_bf16 v[102:105], v[244:247], v[6:9], v[102:105]
	s_waitcnt lgkmcnt(0)
	v_mfma_f32_16x16x32_bf16 v[110:113], v[198:201], v[6:9], v[110:113]
	v_mfma_f32_16x16x32_bf16 v[90:93], v[220:223], v[10:13], 0
	v_mfma_f32_16x16x32_bf16 v[94:97], v[224:227], v[10:13], 0
	v_mfma_f32_16x16x32_bf16 v[82:85], v[228:231], v[10:13], 0
	v_mfma_f32_16x16x32_bf16 v[86:89], v[232:235], v[10:13], 0
	v_fmamk_f32 v74, v98, 0x3fb8aa3b, v217
	v_fmamk_f32 v75, v99, 0x3fb8aa3b, v217
	v_mfma_f32_16x16x32_bf16 v[90:93], v[236:239], v[14:17], v[90:93]
	v_fmamk_f32 v76, v100, 0x3fb8aa3b, v217
	v_fmamk_f32 v77, v101, 0x3fb8aa3b, v217
	v_mfma_f32_16x16x32_bf16 v[94:97], v[240:243], v[14:17], v[94:97]
	v_fmamk_f32 v78, v106, 0x3fb8aa3b, v217
	v_fmamk_f32 v79, v107, 0x3fb8aa3b, v217
	v_mfma_f32_16x16x32_bf16 v[82:85], v[244:247], v[14:17], v[82:85]
	v_fmamk_f32 v80, v108, 0x3fb8aa3b, v217
	v_fmamk_f32 v81, v109, 0x3fb8aa3b, v217
	v_mfma_f32_16x16x32_bf16 v[86:89], v[198:201], v[14:17], v[86:89]
	ds_read_b64 v[220:221], v207 offset:57344
	v_fmamk_f32 v164, v102, 0x3fb8aa3b, v217
	ds_read_b64 v[222:223], v208 offset:57344
	v_fmamk_f32 v165, v103, 0x3fb8aa3b, v217
	ds_read_b64 v[224:225], v209 offset:57344
	v_fmamk_f32 v166, v104, 0x3fb8aa3b, v217
	ds_read_b64 v[226:227], v210 offset:57344
	v_fmamk_f32 v167, v105, 0x3fb8aa3b, v217
	ds_read_b64 v[228:229], v207 offset:59392
	v_fmamk_f32 v168, v110, 0x3fb8aa3b, v217
	ds_read_b64 v[230:231], v208 offset:59392
	v_fmamk_f32 v169, v111, 0x3fb8aa3b, v217
	ds_read_b64 v[232:233], v209 offset:59392
	v_fmamk_f32 v170, v112, 0x3fb8aa3b, v217
	ds_read_b64 v[234:235], v210 offset:59392
	v_fmamk_f32 v171, v113, 0x3fb8aa3b, v217
	ds_read_b64 v[236:237], v207 offset:61440
	v_exp_f32_e32 v74, v74
	ds_read_b64 v[238:239], v208 offset:61440
	v_exp_f32_e32 v75, v75
	ds_read_b64 v[240:241], v209 offset:61440
	v_exp_f32_e32 v76, v76
	ds_read_b64 v[242:243], v210 offset:61440
	v_exp_f32_e32 v77, v77
	ds_read_b64 v[244:245], v211 offset:57344
	v_exp_f32_e32 v78, v78
	ds_read_b64 v[246:247], v212 offset:57344
	v_exp_f32_e32 v79, v79
	ds_read_b64 v[198:199], v213 offset:57344
	v_exp_f32_e32 v80, v80
	ds_read_b64 v[200:201], v214 offset:57344
	v_exp_f32_e32 v81, v81
	v_exp_f32_e32 v164, v164
	v_exp_f32_e32 v165, v165
	v_exp_f32_e32 v166, v166
	v_exp_f32_e32 v167, v167
	v_exp_f32_e32 v168, v168
	v_exp_f32_e32 v169, v169
	v_exp_f32_e32 v170, v170
	v_exp_f32_e32 v171, v171
	v_cvt_pk_bf16_f32 v74, v74, v75
	v_cvt_pk_bf16_f32 v75, v76, v77
	v_cvt_pk_bf16_f32 v76, v78, v79
	v_cvt_pk_bf16_f32 v77, v80, v81
	v_cvt_pk_bf16_f32 v78, v164, v165
	v_cvt_pk_bf16_f32 v79, v166, v167
	v_cvt_pk_bf16_f32 v80, v168, v169
	v_cvt_pk_bf16_f32 v81, v170, v171
	s_waitcnt lgkmcnt(0)
	v_fmamk_f32 v164, v90, 0x3fb8aa3b, v217
	v_fmamk_f32 v165, v91, 0x3fb8aa3b, v217
	v_fmamk_f32 v166, v92, 0x3fb8aa3b, v217
	v_mfma_f32_16x16x32_bf16 v[50:53], v[220:223], v[74:77], v[50:53]
	v_fmamk_f32 v167, v93, 0x3fb8aa3b, v217
	v_mfma_f32_16x16x32_bf16 v[42:45], v[228:231], v[74:77], v[42:45]
	v_fmamk_f32 v168, v94, 0x3fb8aa3b, v217
	v_fmamk_f32 v169, v95, 0x3fb8aa3b, v217
	v_mfma_f32_16x16x32_bf16 v[38:41], v[236:239], v[74:77], v[38:41]
	v_fmamk_f32 v170, v96, 0x3fb8aa3b, v217
	v_fmamk_f32 v171, v97, 0x3fb8aa3b, v217
	v_fmamk_f32 v172, v82, 0x3fb8aa3b, v217
	v_fmamk_f32 v173, v83, 0x3fb8aa3b, v217
	v_mfma_f32_16x16x32_bf16 v[34:37], v[244:247], v[74:77], v[34:37]
	v_fmamk_f32 v174, v84, 0x3fb8aa3b, v217
	v_fmamk_f32 v175, v85, 0x3fb8aa3b, v217
	v_fmamk_f32 v176, v86, 0x3fb8aa3b, v217
	v_fmamk_f32 v177, v87, 0x3fb8aa3b, v217
	v_mfma_f32_16x16x32_bf16 v[50:53], v[224:227], v[78:81], v[50:53]
	v_fmamk_f32 v178, v88, 0x3fb8aa3b, v217
	v_fmamk_f32 v179, v89, 0x3fb8aa3b, v217
	v_exp_f32_e32 v164, v164
	v_exp_f32_e32 v165, v165
	v_mfma_f32_16x16x32_bf16 v[42:45], v[232:235], v[78:81], v[42:45]
	v_exp_f32_e32 v166, v166
	v_exp_f32_e32 v167, v167
	v_exp_f32_e32 v168, v168
	v_exp_f32_e32 v169, v169
	v_mfma_f32_16x16x32_bf16 v[38:41], v[240:243], v[78:81], v[38:41]
	v_exp_f32_e32 v170, v170
	v_exp_f32_e32 v171, v171
	v_exp_f32_e32 v172, v172
	v_exp_f32_e32 v173, v173
	v_mfma_f32_16x16x32_bf16 v[34:37], v[198:201], v[78:81], v[34:37]
	v_exp_f32_e32 v174, v174
	v_exp_f32_e32 v175, v175
	v_exp_f32_e32 v176, v176
	v_exp_f32_e32 v177, v177
	v_mfma_f32_16x16x32_bf16 v[54:57], v[58:61], v[74:77], v[54:57]
	v_exp_f32_e32 v178, v178
	v_exp_f32_e32 v179, v179
	v_cvt_pk_bf16_f32 v82, v164, v165
	v_cvt_pk_bf16_f32 v83, v166, v167
	v_mfma_f32_16x16x32_bf16 v[54:57], v[58:61], v[78:81], v[54:57]
	v_cvt_pk_bf16_f32 v84, v168, v169
	v_cvt_pk_bf16_f32 v85, v170, v171
	v_cvt_pk_bf16_f32 v86, v172, v173
	v_cvt_pk_bf16_f32 v87, v174, v175
	v_cvt_pk_bf16_f32 v88, v176, v177
	v_cvt_pk_bf16_f32 v89, v178, v179
	s_nop 1
	v_mfma_f32_16x16x32_bf16 v[30:33], v[220:223], v[82:85], v[30:33]
	v_mfma_f32_16x16x32_bf16 v[26:29], v[228:231], v[82:85], v[26:29]
	v_mfma_f32_16x16x32_bf16 v[22:25], v[236:239], v[82:85], v[22:25]
	v_mfma_f32_16x16x32_bf16 v[18:21], v[244:247], v[82:85], v[18:21]
	v_mfma_f32_16x16x32_bf16 v[30:33], v[224:227], v[86:89], v[30:33]
	v_mfma_f32_16x16x32_bf16 v[26:29], v[232:235], v[86:89], v[26:29]
	v_mfma_f32_16x16x32_bf16 v[22:25], v[240:243], v[86:89], v[22:25]
	v_mfma_f32_16x16x32_bf16 v[18:21], v[198:201], v[86:89], v[18:21]
	v_mfma_f32_16x16x32_bf16 v[46:49], v[58:61], v[82:85], v[46:49]
	v_mfma_f32_16x16x32_bf16 v[46:49], v[58:61], v[86:89], v[46:49]
	s_branch .LBB0_667_p1

; template <bool FX>
; DI void nsa_tile(const Params& p, int b, int g, int tile, bf16_t* lds, const float CL) {
;     ...
;       for (int s = 0; s <= cur; ++s) {
;         __syncthreads();
;         tile64_sstore(tid, Ks, rk0, rk1);
;         tile64_sstore(tid, Vs, rv0, rv1);
;         __syncthreads();
;         if (s < cur) {
;           tile64_gload(tid, rk0, rk1, kb + (size_t)(s + 1) * 64 * ZS, ZS);
;           tile64_gload(tid, rv0, rv1, vsT + (s + 1) * 64, TS);
;         }
;         uint32_t wsel = (s < 32) ? sw0 : (s < 64) ? sw1 : (s < 96) ? sw2 : sw3;
;         bool sel = (wsel >> (s & 31)) & 1u;
;         int hi = sel ? (tok - s * 64) : -1;
;         if (__any(hi >= 0)) attn_compute<2, FX>(lane, Ks, Vs, qf, st, invl, 0, hi, dA, dE, CL);
.Lnsa_mk_p1:
	v_and_b32_e32 v74, 1, v72
	v_lshrrev_b32_e32 v72, 1, v72
	v_cmp_eq_u32_e32 vcc, 1, v74
	s_nop 1
	v_cndmask_b32_e32 v215, -1, v187, vcc
	v_cmp_lt_i32_e32 vcc, 62, v215
	v_cmp_lt_u32_e64 s[84:85], 62, v215
	s_nop 0
	v_cndmask_b32_e32 v217, v197, v205, vcc
	v_cmp_lt_i32_e32 vcc, -1, v215
	s_cmp_ge_u32 s68, s25
	s_waitcnt vmcnt(0)
	s_barrier
	s_cbranch_scc1 .LBB0_670_p1
	s_mov_b32 m0, s76
	s_add_u32 s86, s76, 0x1000
	global_load_lds_dwordx4 v62, s[80:81]
	s_mov_b32 m0, s86
	s_add_u32 s86, s76, 0x2000
	global_load_lds_dwordx4 v63, s[80:81]
	s_mov_b32 m0, s86
	s_add_u32 s86, s76, 0x3000
	global_load_lds_dwordx4 v64, s[82:83]
	s_mov_b32 m0, s86
	s_add_u32 s80, s80, s22
	global_load_lds_dwordx4 v65, s[82:83]
	s_addc_u32 s81, s81, s23
	s_add_u32 s82, s82, 0x80
	s_addc_u32 s83, s83, 0
	s_xor_b32 s76, s76, 0xc000
; DI f32x4 mfma16(bf16x8 a, bf16x8 b, f32x4 c) { return __builtin_amdgcn_mfma_f32_16x16x32_bf16(a, b, c, 0, 0, 0); }
; template <int MODE, bool FX>
; DI void attn_compute(const int lane, const bf16_t* Ks, const bf16_t* Vs, const bf16x8 (&qf)[2][2], AttnSt& st, const float (&invl)[2],
;                      int lo, int hi, float (&impA)[4], float (&impE)[4], const float CL) {
;     ...
;   for (int ks = 0; ks < 2; ++ks) {
; #pragma unroll
;     for (int kt = 0; kt < 4; ++kt) {
;       int row = kt * 16 + col;
;       bf16x8 kf = *(const bf16x8*)(Ks + row * 64 + (((ks * 4 + quad) ^ ((row >> 1) & 7)) << 3));
; #pragma unroll
;       for (int hh = 0; hh < 2; ++hh) S[kt][hh] = mfma16(kf, qf[hh][ks], S[kt][hh]);
;     }
;   }
;   bf16x8 pf[2][2];
;   const bool full = (lo <= 0) && (hi >= 63);
;   const bool none = (hi < 0) || (lo > 63) || (hi < lo);
;     ...
;     if (FX) {
;       constexpr float L2E = 1.4426950408889634f;
;       const float il = (MODE == 1) ? invl[hh] : 1.f;
;       float rs = 0.f;
; #pragma unroll
;       for (int kt = 0; kt < 4; ++kt) {
;         float a = 0.f;
; #pragma unroll
;         for (int j = 0; j < 4; ++j) {
;           const int kl = kt * 16 + quad * 4 + j;
;           const bool v = (kl >= lo) && (kl <= hi);
;           float pv = v ? __builtin_amdgcn_exp2f(fmaf(S[kt][hh][j], L2E, -CL)) : 0.f;
;           if (MODE == 1) pv *= il;
;           S[kt][hh][j] = pv;
;           a += pv;
;         }
;         rs += a;
;         if (MODE == 1) {
;           impA[kt] += a;
;           impE[kt] += S[kt][hh][3];
;         }
;       }
.LBB0_670_p1:
	s_cbranch_vccz .LBB0_667_p1
	ds_read_b128 v[220:223], v188 offset:49152
	ds_read_b128 v[224:227], v188 offset:51200
	ds_read_b128 v[228:231], v188 offset:53248
	ds_read_b128 v[232:235], v189 offset:49152
	ds_read_b128 v[236:239], v190 offset:49152
	ds_read_b128 v[240:243], v190 offset:51200
	ds_read_b128 v[244:247], v190 offset:53248
	ds_read_b128 v[198:201], v191 offset:49152
	s_cmp_eq_u64 s[84:85], exec
	s_cbranch_scc1 .Lnsa_fast_p1
	s_mov_b64 s[2:3], -1
	s_waitcnt lgkmcnt(7)
	v_mfma_f32_16x16x32_bf16 v[98:101], v[220:223], v[2:5], 0
	v_mfma_f32_16x16x32_bf16 v[90:93], v[220:223], v[10:13], 0
	s_waitcnt lgkmcnt(6)
	v_mfma_f32_16x16x32_bf16 v[106:109], v[224:227], v[2:5], 0
	v_mfma_f32_16x16x32_bf16 v[94:97], v[224:227], v[10:13], 0
	s_waitcnt lgkmcnt(5)
	v_mfma_f32_16x16x32_bf16 v[102:105], v[228:231], v[2:5], 0
	v_mfma_f32_16x16x32_bf16 v[82:85], v[228:231], v[10:13], 0
	s_waitcnt lgkmcnt(4)
	v_mfma_f32_16x16x32_bf16 v[110:113], v[232:235], v[2:5], 0
	v_mfma_f32_16x16x32_bf16 v[86:89], v[232:235], v[10:13], 0
	s_waitcnt lgkmcnt(3)
	v_mfma_f32_16x16x32_bf16 v[98:101], v[236:239], v[6:9], v[98:101]
	v_mfma_f32_16x16x32_bf16 v[90:93], v[236:239], v[14:17], v[90:93]
	s_waitcnt lgkmcnt(2)
	v_mfma_f32_16x16x32_bf16 v[106:109], v[240:243], v[6:9], v[106:109]
	v_mfma_f32_16x16x32_bf16 v[94:97], v[240:243], v[14:17], v[94:97]
	s_waitcnt lgkmcnt(1)
	v_mfma_f32_16x16x32_bf16 v[102:105], v[244:247], v[6:9], v[102:105]
	v_mfma_f32_16x16x32_bf16 v[82:85], v[244:247], v[14:17], v[82:85]
	s_waitcnt lgkmcnt(0)
	v_mfma_f32_16x16x32_bf16 v[110:113], v[198:201], v[6:9], v[110:113]
	v_mfma_f32_16x16x32_bf16 v[86:89], v[198:201], v[14:17], v[86:89]
	ds_read_b64 v[220:221], v207 offset:57344
	ds_read_b64 v[222:223], v208 offset:57344
	ds_read_b64 v[224:225], v209 offset:57344
	ds_read_b64 v[226:227], v210 offset:57344
	ds_read_b64 v[228:229], v207 offset:59392
	ds_read_b64 v[230:231], v208 offset:59392
	ds_read_b64 v[232:233], v209 offset:59392
	ds_read_b64 v[234:235], v210 offset:59392
	ds_read_b64 v[236:237], v207 offset:61440
	ds_read_b64 v[238:239], v208 offset:61440
	ds_read_b64 v[240:241], v209 offset:61440
	ds_read_b64 v[242:243], v210 offset:61440
	ds_read_b64 v[244:245], v211 offset:57344
	ds_read_b64 v[246:247], v212 offset:57344
	ds_read_b64 v[198:199], v213 offset:57344
	ds_read_b64 v[200:201], v214 offset:57344
	s_cbranch_scc1 .LBB0_673_p1
	v_fmamk_f32 v74, v98, 0x3fb8aa3b, v205
	v_fmamk_f32 v75, v99, 0x3fb8aa3b, v205
	v_fmamk_f32 v76, v100, 0x3fb8aa3b, v205
	v_fmamk_f32 v77, v101, 0x3fb8aa3b, v205
	v_fmamk_f32 v78, v106, 0x3fb8aa3b, v205
	v_fmamk_f32 v79, v107, 0x3fb8aa3b, v205
	v_fmamk_f32 v80, v108, 0x3fb8aa3b, v205
	v_fmamk_f32 v81, v109, 0x3fb8aa3b, v205
	v_fmamk_f32 v164, v102, 0x3fb8aa3b, v205
	v_fmamk_f32 v165, v103, 0x3fb8aa3b, v205
	v_fmamk_f32 v166, v104, 0x3fb8aa3b, v205
	v_fmamk_f32 v167, v105, 0x3fb8aa3b, v205
	v_fmamk_f32 v168, v110, 0x3fb8aa3b, v205
	v_fmamk_f32 v169, v111, 0x3fb8aa3b, v205
	v_fmamk_f32 v170, v112, 0x3fb8aa3b, v205
	v_fmamk_f32 v171, v113, 0x3fb8aa3b, v205
	v_exp_f32_e32 v74, v74
	v_exp_f32_e32 v75, v75
	v_exp_f32_e32 v76, v76
	v_exp_f32_e32 v77, v77
	v_exp_f32_e32 v78, v78
	v_exp_f32_e32 v79, v79
	v_exp_f32_e32 v80, v80
	v_exp_f32_e32 v81, v81
	v_exp_f32_e32 v164, v164
	v_exp_f32_e32 v165, v165
	v_exp_f32_e32 v166, v166
	v_exp_f32_e32 v167, v167
	v_exp_f32_e32 v168, v168
	v_exp_f32_e32 v169, v169
	v_exp_f32_e32 v170, v170
	v_exp_f32_e32 v171, v171
	v_cmp_gt_i32_e32 vcc, v118, v215
	v_cmp_lt_i32_e64 s[2:3], v118, v215
	v_cmp_gt_i32_e64 s[52:53], v119, v215
	v_cmp_gt_i32_e64 s[54:55], v192, v215
	v_cmp_gt_i32_e64 s[40:41], v120, v215
	v_cmp_gt_i32_e64 s[42:43], v193, v215
	v_cmp_gt_i32_e64 s[56:57], v122, v215
	v_cmp_gt_i32_e64 s[58:59], v121, v215
	v_cmp_gt_i32_e64 s[44:45], v194, v215
	v_cmp_gt_i32_e64 s[46:47], v195, v215
	v_cmp_gt_i32_e64 s[60:61], v206, v215
	v_cmp_gt_i32_e64 s[62:63], v124, v215
	v_cmp_gt_i32_e64 s[48:49], v126, v215
	v_cmp_gt_i32_e64 s[50:51], v123, v215
	v_cmp_gt_i32_e64 s[64:65], v125, v215
	v_cmp_gt_i32_e64 s[66:67], v127, v215
	v_cndmask_b32_e64 v74, v74, 0, vcc
	v_cndmask_b32_e64 v75, 0, v75, s[2:3]
	v_cndmask_b32_e64 v76, v76, 0, s[52:53]
	v_cndmask_b32_e64 v77, v77, 0, s[54:55]
	v_cndmask_b32_e64 v78, v78, 0, s[40:41]
	v_cndmask_b32_e64 v79, v79, 0, s[42:43]
	v_cndmask_b32_e64 v80, v80, 0, s[56:57]
	v_cndmask_b32_e64 v81, v81, 0, s[58:59]
	v_cndmask_b32_e64 v164, v164, 0, s[44:45]
	v_cndmask_b32_e64 v165, v165, 0, s[46:47]
	v_cndmask_b32_e64 v166, v166, 0, s[60:61]
	v_cndmask_b32_e64 v167, v167, 0, s[62:63]
	v_cndmask_b32_e64 v168, v168, 0, s[48:49]
	v_cndmask_b32_e64 v169, v169, 0, s[50:51]
	v_cndmask_b32_e64 v170, v170, 0, s[64:65]
	v_cndmask_b32_e64 v171, v171, 0, s[66:67]
	v_cvt_pk_bf16_f32 v74, v74, v75
	v_cvt_pk_bf16_f32 v75, v76, v77
	v_cvt_pk_bf16_f32 v76, v78, v79
	v_cvt_pk_bf16_f32 v77, v80, v81
	v_cvt_pk_bf16_f32 v78, v164, v165
	v_cvt_pk_bf16_f32 v79, v166, v167
	v_cvt_pk_bf16_f32 v80, v168, v169
	v_cvt_pk_bf16_f32 v81, v170, v171
	v_fmamk_f32 v164, v90, 0x3fb8aa3b, v205
	v_fmamk_f32 v165, v91, 0x3fb8aa3b, v205
	v_fmamk_f32 v166, v92, 0x3fb8aa3b, v205
	v_fmamk_f32 v167, v93, 0x3fb8aa3b, v205
	v_fmamk_f32 v168, v94, 0x3fb8aa3b, v205
	v_fmamk_f32 v169, v95, 0x3fb8aa3b, v205
	v_fmamk_f32 v170, v96, 0x3fb8aa3b, v205
	v_fmamk_f32 v171, v97, 0x3fb8aa3b, v205
	v_fmamk_f32 v172, v82, 0x3fb8aa3b, v205
	v_fmamk_f32 v173, v83, 0x3fb8aa3b, v205
	v_fmamk_f32 v174, v84, 0x3fb8aa3b, v205
	v_fmamk_f32 v175, v85, 0x3fb8aa3b, v205
	v_fmamk_f32 v176, v86, 0x3fb8aa3b, v205
	v_fmamk_f32 v177, v87, 0x3fb8aa3b, v205
	v_fmamk_f32 v178, v88, 0x3fb8aa3b, v205
	v_fmamk_f32 v179, v89, 0x3fb8aa3b, v205
	v_exp_f32_e32 v164, v164
	v_exp_f32_e32 v165, v165
	v_exp_f32_e32 v166, v166
	v_exp_f32_e32 v167, v167
	v_exp_f32_e32 v168, v168
	v_exp_f32_e32 v169, v169
	v_exp_f32_e32 v170, v170
	v_exp_f32_e32 v171, v171
	v_exp_f32_e32 v172, v172
	v_exp_f32_e32 v173, v173
	v_exp_f32_e32 v174, v174
	v_exp_f32_e32 v175, v175
	v_exp_f32_e32 v176, v176
	v_exp_f32_e32 v177, v177
	v_exp_f32_e32 v178, v178
	v_exp_f32_e32 v179, v179
	v_cndmask_b32_e64 v164, v164, 0, vcc
	v_cndmask_b32_e64 v165, 0, v165, s[2:3]
	v_cndmask_b32_e64 v166, v166, 0, s[52:53]
	v_cndmask_b32_e64 v167, v167, 0, s[54:55]
	v_cndmask_b32_e64 v168, v168, 0, s[40:41]
	v_cndmask_b32_e64 v169, v169, 0, s[42:43]
	v_cndmask_b32_e64 v170, v170, 0, s[56:57]
	v_cndmask_b32_e64 v171, v171, 0, s[58:59]
	v_cndmask_b32_e64 v172, v172, 0, s[44:45]
	v_cndmask_b32_e64 v173, v173, 0, s[46:47]
	v_cndmask_b32_e64 v174, v174, 0, s[60:61]
	v_cndmask_b32_e64 v175, v175, 0, s[62:63]
	v_cndmask_b32_e64 v176, v176, 0, s[48:49]
	v_cndmask_b32_e64 v177, v177, 0, s[50:51]
	v_cndmask_b32_e64 v178, v178, 0, s[64:65]
	v_cndmask_b32_e64 v179, v179, 0, s[66:67]
	s_mov_b64 s[2:3], 0

; template <int MODE, bool FX>
; DI void attn_compute(const int lane, const bf16_t* Ks, const bf16_t* Vs, const bf16x8 (&qf)[2][2], AttnSt& st, const float (&invl)[2],
;                      int lo, int hi, float (&impA)[4], float (&impE)[4], const float CL) {
;     ...
;   for (int ks = 0; ks < 2; ++ks) {
; #pragma unroll
;     for (int kt = 0; kt < 4; ++kt) {
;       int row = kt * 16 + col;
;       bf16x8 kf = *(const bf16x8*)(Ks + row * 64 + (((ks * 4 + quad) ^ ((row >> 1) & 7)) << 3));
; #pragma unroll
;       for (int hh = 0; hh < 2; ++hh) S[kt][hh] = mfma16(kf, qf[hh][ks], S[kt][hh]);
;     }
;   }
;   bf16x8 pf[2][2];
;   const bool full = (lo <= 0) && (hi >= 63);
;   const bool none = (hi < 0) || (lo > 63) || (hi < lo);
;   if (__all(full || none)) {
;     constexpr float L2E = 1.4426950408889634f;
; #pragma unroll
;     for (int hh = 0; hh < 2; ++hh) {
;       float mL;
;       float il = 1.f;
;       if (FX) {
;         mL = full ? CL : 1e30f;
;         if (MODE == 1) il = invl[hh];
;       } else if (MODE != 1) {
;         float mx = -1e30f;
; #pragma unroll
;         for (int kt = 0; kt < 4; ++kt)
; #pragma unroll
;           for (int j = 0; j < 4; ++j) mx = fmaxf(mx, S[kt][hh][j]);
;         mx = full ? mx : -1e30f;
;         mx = fmaxf(mx, shx(mx, 16, lane));
;         mx = fmaxf(mx, shx(mx, 32, lane));
;         const float m_new = fmaxf(st.m[hh], mx);
;         const float alpha = __expf(st.m[hh] - m_new);
;         st.m[hh] = m_new;
;         st.l[hh] *= alpha;
;         if (MODE == 2) {
; #pragma unroll
;           for (int dt = 0; dt < 4; ++dt) st.O[hh][dt] *= alpha;
;         }
;         mL = full ? m_new * L2E : 1e30f;
;       } else {
;         mL = full ? st.m[hh] * L2E : 1e30f;
;         il = invl[hh];
;       }
;       float rs = 0.f;
; #pragma unroll
;       for (int kt = 0; kt < 4; ++kt) {
;         float a = 0.f;
; #pragma unroll
;         for (int j = 0; j < 4; ++j) {
;           float pv = __builtin_amdgcn_exp2f(fmaf(S[kt][hh][j], L2E, -mL));
;           if (MODE == 1) pv *= il;
;           S[kt][hh][j] = pv;
;           a += pv;
;         }
;     ...
;   if (MODE != 0) {
; #pragma unroll
;     for (int dt = 0; dt < 4; ++dt) {
;       const int row = dt * 16 + col;
;       const int sw = (row >> 1) & 7;
; #pragma unroll
;       for (int c = 0; c < 2; ++c) {
.Lnsa_fast:
	s_waitcnt lgkmcnt(7)
	v_mfma_f32_16x16x32_bf16 v[98:101], v[220:223], v[2:5], 0
	s_waitcnt lgkmcnt(6)
	v_mfma_f32_16x16x32_bf16 v[106:109], v[224:227], v[2:5], 0
	s_waitcnt lgkmcnt(5)
	v_mfma_f32_16x16x32_bf16 v[102:105], v[228:231], v[2:5], 0
	s_waitcnt lgkmcnt(4)
	v_mfma_f32_16x16x32_bf16 v[110:113], v[232:235], v[2:5], 0
	s_waitcnt lgkmcnt(3)
	v_mfma_f32_16x16x32_bf16 v[98:101], v[236:239], v[6:9], v[98:101]
	s_waitcnt lgkmcnt(2)
	v_mfma_f32_16x16x32_bf16 v[106:109], v[240:243], v[6:9], v[106:109]
	s_waitcnt lgkmcnt(1)
	v_mfma_f32_16x16x32_bf16 v[102:105], v[244:247], v[6:9], v[102:105]
	s_waitcnt lgkmcnt(0)
	v_mfma_f32_16x16x32_bf16 v[110:113], v[198:201], v[6:9], v[110:113]
	v_mfma_f32_16x16x32_bf16 v[90:93], v[220:223], v[10:13], 0
	v_mfma_f32_16x16x32_bf16 v[94:97], v[224:227], v[10:13], 0
	v_mfma_f32_16x16x32_bf16 v[82:85], v[228:231], v[10:13], 0
	v_mfma_f32_16x16x32_bf16 v[86:89], v[232:235], v[10:13], 0
	v_fmamk_f32 v74, v98, 0x3fb8aa3b, v217
	v_fmamk_f32 v75, v99, 0x3fb8aa3b, v217
	v_mfma_f32_16x16x32_bf16 v[90:93], v[236:239], v[14:17], v[90:93]
	v_fmamk_f32 v76, v100, 0x3fb8aa3b, v217
	v_fmamk_f32 v77, v101, 0x3fb8aa3b, v217
	v_mfma_f32_16x16x32_bf16 v[94:97], v[240:243], v[14:17], v[94:97]
	v_fmamk_f32 v78, v106, 0x3fb8aa3b, v217
	v_fmamk_f32 v79, v107, 0x3fb8aa3b, v217
	v_mfma_f32_16x16x32_bf16 v[82:85], v[244:247], v[14:17], v[82:85]
	v_fmamk_f32 v80, v108, 0x3fb8aa3b, v217
	v_fmamk_f32 v81, v109, 0x3fb8aa3b, v217
	v_mfma_f32_16x16x32_bf16 v[86:89], v[198:201], v[14:17], v[86:89]
	ds_read_b64 v[220:221], v207 offset:8192
	v_fmamk_f32 v164, v102, 0x3fb8aa3b, v217
	ds_read_b64 v[222:223], v208 offset:8192
	v_fmamk_f32 v165, v103, 0x3fb8aa3b, v217
	ds_read_b64 v[224:225], v209 offset:8192
	v_fmamk_f32 v166, v104, 0x3fb8aa3b, v217
	ds_read_b64 v[226:227], v210 offset:8192
	v_fmamk_f32 v167, v105, 0x3fb8aa3b, v217
	ds_read_b64 v[228:229], v207 offset:10240
	v_fmamk_f32 v168, v110, 0x3fb8aa3b, v217
	ds_read_b64 v[230:231], v208 offset:10240
	v_fmamk_f32 v169, v111, 0x3fb8aa3b, v217
	ds_read_b64 v[232:233], v209 offset:10240
	v_fmamk_f32 v170, v112, 0x3fb8aa3b, v217
	ds_read_b64 v[234:235], v210 offset:10240
	v_fmamk_f32 v171, v113, 0x3fb8aa3b, v217
	ds_read_b64 v[236:237], v207 offset:12288
	v_exp_f32_e32 v74, v74
	ds_read_b64 v[238:239], v208 offset:12288
	v_exp_f32_e32 v75, v75
	ds_read_b64 v[240:241], v209 offset:12288
	v_exp_f32_e32 v76, v76
	ds_read_b64 v[242:243], v210 offset:12288
	v_exp_f32_e32 v77, v77
	ds_read_b64 v[244:245], v211 offset:8192
	v_exp_f32_e32 v78, v78
	ds_read_b64 v[246:247], v212 offset:8192
	v_exp_f32_e32 v79, v79
	ds_read_b64 v[198:199], v213 offset:8192
	v_exp_f32_e32 v80, v80
	ds_read_b64 v[200:201], v214 offset:8192
	v_exp_f32_e32 v81, v81
	v_exp_f32_e32 v164, v164
	v_exp_f32_e32 v165, v165
	v_exp_f32_e32 v166, v166
	v_exp_f32_e32 v167, v167
	v_exp_f32_e32 v168, v168
	v_exp_f32_e32 v169, v169
	v_exp_f32_e32 v170, v170
	v_exp_f32_e32 v171, v171
	v_cvt_pk_bf16_f32 v74, v74, v75
	v_cvt_pk_bf16_f32 v75, v76, v77
	v_cvt_pk_bf16_f32 v76, v78, v79
	v_cvt_pk_bf16_f32 v77, v80, v81
	v_cvt_pk_bf16_f32 v78, v164, v165
	v_cvt_pk_bf16_f32 v79, v166, v167
	v_cvt_pk_bf16_f32 v80, v168, v169
	v_cvt_pk_bf16_f32 v81, v170, v171
	s_waitcnt lgkmcnt(0)
	v_fmamk_f32 v164, v90, 0x3fb8aa3b, v217
	v_fmamk_f32 v165, v91, 0x3fb8aa3b, v217
	v_fmamk_f32 v166, v92, 0x3fb8aa3b, v217
	v_mfma_f32_16x16x32_bf16 v[50:53], v[220:223], v[74:77], v[50:53]
	v_fmamk_f32 v167, v93, 0x3fb8aa3b, v217
	v_mfma_f32_16x16x32_bf16 v[42:45], v[228:231], v[74:77], v[42:45]
	v_fmamk_f32 v168, v94, 0x3fb8aa3b, v217
	v_fmamk_f32 v169, v95, 0x3fb8aa3b, v217
	v_mfma_f32_16x16x32_bf16 v[38:41], v[236:239], v[74:77], v[38:41]
	v_fmamk_f32 v170, v96, 0x3fb8aa3b, v217
	v_fmamk_f32 v171, v97, 0x3fb8aa3b, v217
	v_fmamk_f32 v172, v82, 0x3fb8aa3b, v217
	v_fmamk_f32 v173, v83, 0x3fb8aa3b, v217
	v_mfma_f32_16x16x32_bf16 v[34:37], v[244:247], v[74:77], v[34:37]
	v_fmamk_f32 v174, v84, 0x3fb8aa3b, v217
	v_fmamk_f32 v175, v85, 0x3fb8aa3b, v217
	v_fmamk_f32 v176, v86, 0x3fb8aa3b, v217
	v_fmamk_f32 v177, v87, 0x3fb8aa3b, v217
	v_mfma_f32_16x16x32_bf16 v[50:53], v[224:227], v[78:81], v[50:53]
	v_fmamk_f32 v178, v88, 0x3fb8aa3b, v217
	v_fmamk_f32 v179, v89, 0x3fb8aa3b, v217
	v_exp_f32_e32 v164, v164
	v_exp_f32_e32 v165, v165
	v_mfma_f32_16x16x32_bf16 v[42:45], v[232:235], v[78:81], v[42:45]
	v_exp_f32_e32 v166, v166
	v_exp_f32_e32 v167, v167
	v_exp_f32_e32 v168, v168
	v_exp_f32_e32 v169, v169
	v_mfma_f32_16x16x32_bf16 v[38:41], v[240:243], v[78:81], v[38:41]
	v_exp_f32_e32 v170, v170
	v_exp_f32_e32 v171, v171
	v_exp_f32_e32 v172, v172
	v_exp_f32_e32 v173, v173
	v_mfma_f32_16x16x32_bf16 v[34:37], v[198:201], v[78:81], v[34:37]
	v_exp_f32_e32 v174, v174
	v_exp_f32_e32 v175, v175
	v_exp_f32_e32 v176, v176
	v_exp_f32_e32 v177, v177
	v_mfma_f32_16x16x32_bf16 v[54:57], v[58:61], v[74:77], v[54:57]
	v_exp_f32_e32 v178, v178
	v_exp_f32_e32 v179, v179
	v_cvt_pk_bf16_f32 v82, v164, v165
	v_cvt_pk_bf16_f32 v83, v166, v167
	v_mfma_f32_16x16x32_bf16 v[54:57], v[58:61], v[78:81], v[54:57]
	v_cvt_pk_bf16_f32 v84, v168, v169
	v_cvt_pk_bf16_f32 v85, v170, v171
	v_cvt_pk_bf16_f32 v86, v172, v173
	v_cvt_pk_bf16_f32 v87, v174, v175
	v_cvt_pk_bf16_f32 v88, v176, v177
	v_cvt_pk_bf16_f32 v89, v178, v179
	s_nop 1
	v_mfma_f32_16x16x32_bf16 v[30:33], v[220:223], v[82:85], v[30:33]
	v_mfma_f32_16x16x32_bf16 v[26:29], v[228:231], v[82:85], v[26:29]
	v_mfma_f32_16x16x32_bf16 v[22:25], v[236:239], v[82:85], v[22:25]
	v_mfma_f32_16x16x32_bf16 v[18:21], v[244:247], v[82:85], v[18:21]
	v_mfma_f32_16x16x32_bf16 v[30:33], v[224:227], v[86:89], v[30:33]
	v_mfma_f32_16x16x32_bf16 v[26:29], v[232:235], v[86:89], v[26:29]
	v_mfma_f32_16x16x32_bf16 v[22:25], v[240:243], v[86:89], v[22:25]
	v_mfma_f32_16x16x32_bf16 v[18:21], v[198:201], v[86:89], v[18:21]
	v_mfma_f32_16x16x32_bf16 v[46:49], v[58:61], v[82:85], v[46:49]
	v_mfma_f32_16x16x32_bf16 v[46:49], v[58:61], v[86:89], v[46:49]
	s_branch .LBB0_667

; DI f32x4 mfma16(bf16x8 a, bf16x8 b, f32x4 c) { return __builtin_amdgcn_mfma_f32_16x16x32_bf16(a, b, c, 0, 0, 0); }
; template <int MODE, bool FX>
; DI void attn_compute(const int lane, const bf16_t* Ks, const bf16_t* Vs, const bf16x8 (&qf)[2][2], AttnSt& st, const float (&invl)[2],
;                      int lo, int hi, float (&impA)[4], float (&impE)[4], const float CL) {
;     ...
;   for (int ks = 0; ks < 2; ++ks) {
; #pragma unroll
;     for (int kt = 0; kt < 4; ++kt) {
;       int row = kt * 16 + col;
;       bf16x8 kf = *(const bf16x8*)(Ks + row * 64 + (((ks * 4 + quad) ^ ((row >> 1) & 7)) << 3));
; #pragma unroll
;       for (int hh = 0; hh < 2; ++hh) S[kt][hh] = mfma16(kf, qf[hh][ks], S[kt][hh]);
;     }
;   }
;   bf16x8 pf[2][2];
;   const bool full = (lo <= 0) && (hi >= 63);
;   const bool none = (hi < 0) || (lo > 63) || (hi < lo);
;     ...
;     if (FX) {
;       constexpr float L2E = 1.4426950408889634f;
;       const float il = (MODE == 1) ? invl[hh] : 1.f;
;       float rs = 0.f;
; #pragma unroll
;       for (int kt = 0; kt < 4; ++kt) {
;         float a = 0.f;
; #pragma unroll
;         for (int j = 0; j < 4; ++j) {
;           const int kl = kt * 16 + quad * 4 + j;
;           const bool v = (kl >= lo) && (kl <= hi);
;           float pv = v ? __builtin_amdgcn_exp2f(fmaf(S[kt][hh][j], L2E, -CL)) : 0.f;
;           if (MODE == 1) pv *= il;
;           S[kt][hh][j] = pv;
;           a += pv;
;         }
;         rs += a;
;         if (MODE == 1) {
;           impA[kt] += a;
;           impE[kt] += S[kt][hh][3];
;         }
;       }
.LBB0_670:
	s_cbranch_vccz .LBB0_667
	ds_read_b128 v[220:223], v188
	ds_read_b128 v[224:227], v188 offset:2048
	ds_read_b128 v[228:231], v188 offset:4096
	ds_read_b128 v[232:235], v189
	ds_read_b128 v[236:239], v190
	ds_read_b128 v[240:243], v190 offset:2048
	ds_read_b128 v[244:247], v190 offset:4096
	ds_read_b128 v[198:201], v191
	s_cmp_eq_u64 s[84:85], exec
	s_cbranch_scc1 .Lnsa_fast
	s_mov_b64 s[2:3], -1
	s_waitcnt lgkmcnt(7)
	v_mfma_f32_16x16x32_bf16 v[98:101], v[220:223], v[2:5], 0
	v_mfma_f32_16x16x32_bf16 v[90:93], v[220:223], v[10:13], 0
	s_waitcnt lgkmcnt(6)
	v_mfma_f32_16x16x32_bf16 v[106:109], v[224:227], v[2:5], 0
	v_mfma_f32_16x16x32_bf16 v[94:97], v[224:227], v[10:13], 0
	s_waitcnt lgkmcnt(5)
	v_mfma_f32_16x16x32_bf16 v[102:105], v[228:231], v[2:5], 0
	v_mfma_f32_16x16x32_bf16 v[82:85], v[228:231], v[10:13], 0
	s_waitcnt lgkmcnt(4)
	v_mfma_f32_16x16x32_bf16 v[110:113], v[232:235], v[2:5], 0
	v_mfma_f32_16x16x32_bf16 v[86:89], v[232:235], v[10:13], 0
	s_waitcnt lgkmcnt(3)
	v_mfma_f32_16x16x32_bf16 v[98:101], v[236:239], v[6:9], v[98:101]
	v_mfma_f32_16x16x32_bf16 v[90:93], v[236:239], v[14:17], v[90:93]
	s_waitcnt lgkmcnt(2)
	v_mfma_f32_16x16x32_bf16 v[106:109], v[240:243], v[6:9], v[106:109]
	v_mfma_f32_16x16x32_bf16 v[94:97], v[240:243], v[14:17], v[94:97]
	s_waitcnt lgkmcnt(1)
	v_mfma_f32_16x16x32_bf16 v[102:105], v[244:247], v[6:9], v[102:105]
	v_mfma_f32_16x16x32_bf16 v[82:85], v[244:247], v[14:17], v[82:85]
	s_waitcnt lgkmcnt(0)
	v_mfma_f32_16x16x32_bf16 v[110:113], v[198:201], v[6:9], v[110:113]
	v_mfma_f32_16x16x32_bf16 v[86:89], v[198:201], v[14:17], v[86:89]
	ds_read_b64 v[220:221], v207 offset:8192
	ds_read_b64 v[222:223], v208 offset:8192
	ds_read_b64 v[224:225], v209 offset:8192
	ds_read_b64 v[226:227], v210 offset:8192
	ds_read_b64 v[228:229], v207 offset:10240
	ds_read_b64 v[230:231], v208 offset:10240
	ds_read_b64 v[232:233], v209 offset:10240
	ds_read_b64 v[234:235], v210 offset:10240
	ds_read_b64 v[236:237], v207 offset:12288
	ds_read_b64 v[238:239], v208 offset:12288
	ds_read_b64 v[240:241], v209 offset:12288
	ds_read_b64 v[242:243], v210 offset:12288
	ds_read_b64 v[244:245], v211 offset:8192
	ds_read_b64 v[246:247], v212 offset:8192
	ds_read_b64 v[198:199], v213 offset:8192
	ds_read_b64 v[200:201], v214 offset:8192
	s_cbranch_scc1 .LBB0_673
	v_fmamk_f32 v74, v98, 0x3fb8aa3b, v205
	v_fmamk_f32 v75, v99, 0x3fb8aa3b, v205
	v_fmamk_f32 v76, v100, 0x3fb8aa3b, v205
	v_fmamk_f32 v77, v101, 0x3fb8aa3b, v205
	v_fmamk_f32 v78, v106, 0x3fb8aa3b, v205
	v_fmamk_f32 v79, v107, 0x3fb8aa3b, v205
	v_fmamk_f32 v80, v108, 0x3fb8aa3b, v205
	v_fmamk_f32 v81, v109, 0x3fb8aa3b, v205
	v_fmamk_f32 v164, v102, 0x3fb8aa3b, v205
	v_fmamk_f32 v165, v103, 0x3fb8aa3b, v205
	v_fmamk_f32 v166, v104, 0x3fb8aa3b, v205
	v_fmamk_f32 v167, v105, 0x3fb8aa3b, v205
	v_fmamk_f32 v168, v110, 0x3fb8aa3b, v205
	v_fmamk_f32 v169, v111, 0x3fb8aa3b, v205
	v_fmamk_f32 v170, v112, 0x3fb8aa3b, v205
	v_fmamk_f32 v171, v113, 0x3fb8aa3b, v205
	v_exp_f32_e32 v74, v74
	v_exp_f32_e32 v75, v75
	v_exp_f32_e32 v76, v76
	v_exp_f32_e32 v77, v77
	v_exp_f32_e32 v78, v78
	v_exp_f32_e32 v79, v79
	v_exp_f32_e32 v80, v80
	v_exp_f32_e32 v81, v81
	v_exp_f32_e32 v164, v164
	v_exp_f32_e32 v165, v165
	v_exp_f32_e32 v166, v166
	v_exp_f32_e32 v167, v167
	v_exp_f32_e32 v168, v168
	v_exp_f32_e32 v169, v169
	v_exp_f32_e32 v170, v170
	v_exp_f32_e32 v171, v171
	v_cmp_gt_i32_e32 vcc, v118, v215
	v_cmp_lt_i32_e64 s[2:3], v118, v215
	v_cmp_gt_i32_e64 s[52:53], v119, v215
	v_cmp_gt_i32_e64 s[54:55], v192, v215
	v_cmp_gt_i32_e64 s[40:41], v120, v215
	v_cmp_gt_i32_e64 s[42:43], v193, v215
	v_cmp_gt_i32_e64 s[56:57], v122, v215
	v_cmp_gt_i32_e64 s[58:59], v121, v215
	v_cmp_gt_i32_e64 s[44:45], v194, v215
	v_cmp_gt_i32_e64 s[46:47], v195, v215
	v_cmp_gt_i32_e64 s[60:61], v206, v215
	v_cmp_gt_i32_e64 s[62:63], v124, v215
	v_cmp_gt_i32_e64 s[48:49], v126, v215
	v_cmp_gt_i32_e64 s[50:51], v123, v215
	v_cmp_gt_i32_e64 s[64:65], v125, v215
	v_cmp_gt_i32_e64 s[66:67], v127, v215
	v_cndmask_b32_e64 v74, v74, 0, vcc
	v_cndmask_b32_e64 v75, 0, v75, s[2:3]
	v_cndmask_b32_e64 v76, v76, 0, s[52:53]
	v_cndmask_b32_e64 v77, v77, 0, s[54:55]
	v_cndmask_b32_e64 v78, v78, 0, s[40:41]
	v_cndmask_b32_e64 v79, v79, 0, s[42:43]
	v_cndmask_b32_e64 v80, v80, 0, s[56:57]
	v_cndmask_b32_e64 v81, v81, 0, s[58:59]
	v_cndmask_b32_e64 v164, v164, 0, s[44:45]
	v_cndmask_b32_e64 v165, v165, 0, s[46:47]
	v_cndmask_b32_e64 v166, v166, 0, s[60:61]
	v_cndmask_b32_e64 v167, v167, 0, s[62:63]
	v_cndmask_b32_e64 v168, v168, 0, s[48:49]
	v_cndmask_b32_e64 v169, v169, 0, s[50:51]
	v_cndmask_b32_e64 v170, v170, 0, s[64:65]
	v_cndmask_b32_e64 v171, v171, 0, s[66:67]
	v_cvt_pk_bf16_f32 v74, v74, v75
	v_cvt_pk_bf16_f32 v75, v76, v77
	v_cvt_pk_bf16_f32 v76, v78, v79
	v_cvt_pk_bf16_f32 v77, v80, v81
	v_cvt_pk_bf16_f32 v78, v164, v165
	v_cvt_pk_bf16_f32 v79, v166, v167
	v_cvt_pk_bf16_f32 v80, v168, v169
	v_cvt_pk_bf16_f32 v81, v170, v171
	v_fmamk_f32 v164, v90, 0x3fb8aa3b, v205
	v_fmamk_f32 v165, v91, 0x3fb8aa3b, v205
	v_fmamk_f32 v166, v92, 0x3fb8aa3b, v205
	v_fmamk_f32 v167, v93, 0x3fb8aa3b, v205
	v_fmamk_f32 v168, v94, 0x3fb8aa3b, v205
	v_fmamk_f32 v169, v95, 0x3fb8aa3b, v205
	v_fmamk_f32 v170, v96, 0x3fb8aa3b, v205
	v_fmamk_f32 v171, v97, 0x3fb8aa3b, v205
	v_fmamk_f32 v172, v82, 0x3fb8aa3b, v205
	v_fmamk_f32 v173, v83, 0x3fb8aa3b, v205
	v_fmamk_f32 v174, v84, 0x3fb8aa3b, v205
	v_fmamk_f32 v175, v85, 0x3fb8aa3b, v205
	v_fmamk_f32 v176, v86, 0x3fb8aa3b, v205
	v_fmamk_f32 v177, v87, 0x3fb8aa3b, v205
	v_fmamk_f32 v178, v88, 0x3fb8aa3b, v205
	v_fmamk_f32 v179, v89, 0x3fb8aa3b, v205
	v_exp_f32_e32 v164, v164
	v_exp_f32_e32 v165, v165
	v_exp_f32_e32 v166, v166
	v_exp_f32_e32 v167, v167
	v_exp_f32_e32 v168, v168
	v_exp_f32_e32 v169, v169
	v_exp_f32_e32 v170, v170
	v_exp_f32_e32 v171, v171
	v_exp_f32_e32 v172, v172
	v_exp_f32_e32 v173, v173
	v_exp_f32_e32 v174, v174
	v_exp_f32_e32 v175, v175
	v_exp_f32_e32 v176, v176
	v_exp_f32_e32 v177, v177
	v_exp_f32_e32 v178, v178
	v_exp_f32_e32 v179, v179
	v_cndmask_b32_e64 v164, v164, 0, vcc
	v_cndmask_b32_e64 v165, 0, v165, s[2:3]
	v_cndmask_b32_e64 v166, v166, 0, s[52:53]
	v_cndmask_b32_e64 v167, v167, 0, s[54:55]
	v_cndmask_b32_e64 v168, v168, 0, s[40:41]
	v_cndmask_b32_e64 v169, v169, 0, s[42:43]
	v_cndmask_b32_e64 v170, v170, 0, s[56:57]
	v_cndmask_b32_e64 v171, v171, 0, s[58:59]
	v_cndmask_b32_e64 v172, v172, 0, s[44:45]
	v_cndmask_b32_e64 v173, v173, 0, s[46:47]
	v_cndmask_b32_e64 v174, v174, 0, s[60:61]
	v_cndmask_b32_e64 v175, v175, 0, s[62:63]
	v_cndmask_b32_e64 v176, v176, 0, s[48:49]
	v_cndmask_b32_e64 v177, v177, 0, s[50:51]
	v_cndmask_b32_e64 v178, v178, 0, s[64:65]
	v_cndmask_b32_e64 v179, v179, 0, s[66:67]
	s_mov_b64 s[2:3], 0

; #pragma unroll
;   for (int ks = KS0; ks < KS1; ++ks) {
;     bf16x8 af[8], bfr[4];
; #pragma unroll
;     for (int i = 0; i < 8; ++i) {
;       const int r = wm * 128 + i * 16 + (lane & 15);
;       af[i] = *(const bf16x8*)(S + r * 64 + (((ks * 4 + (lane >> 4)) ^ ((r >> 1) & 7)) << 3));
;     }
; #pragma unroll
;     for (int j = 0; j < 4; ++j) {
;       const int r = wn * 64 + j * 16 + (lane & 15);
;       bfr[j] = *(const bf16x8*)(S + 16384 + r * 64 + (((ks * 4 + (lane >> 4)) ^ ((r >> 1) & 7)) << 3));
;     }
;     __builtin_amdgcn_s_setprio(1);
; #pragma unroll
;     for (int i = 0; i < 8; ++i)
; #pragma unroll
;       for (int j = 0; j < 4; ++j) acc[i][j] = mfma16(bfr[j], af[i], acc[i][j]);
;     __builtin_amdgcn_s_setprio(0);
;   }
; }
; DI void g8_load1o(u32x4 (&r4)[4], const bf16_t* base, const unsigned (&off)[4]) {
; #pragma unroll
;   for (int i = 0; i < 4; ++i) r4[i] = *(const u32x4*)(base + off[i]);
; }
; DI void gemm8_accum(f32x4 (&acc)[8][4], const bf16_t* a, size_t lda, const bf16_t* b, size_t ldb, int nkb, bf16_t* L,
;                     const bool pre, const bf16_t* an, size_t ldan, const bf16_t* bn, size_t ldbn) {
;   const int tid = TID8(), lane = tid & 63, w = tid >> 6;
;   const int wm = w >> 2, wn = w & 3;
;   const int lrow = tid >> 3, lch = tid & 7;
;   u32x4 ra[4], rb[4];
;   unsigned offa[4], offb[4];
; #pragma unroll
;   for (int i = 0; i < 4; ++i) {
;     offa[i] = (unsigned)(lrow + 64 * i) * (unsigned)lda + (unsigned)(lch * 8);
;     offb[i] = (unsigned)(lrow + 64 * i) * (unsigned)ldb + (unsigned)(lch * 8);
;   }
;   if (!pre) {
;     g8_load1o(ra, a, offa);
;     g8_load1o(rb, b, offb);
;     __syncthreads();
;     g8_store(L, ra, rb, lrow, lch);
;   }
;   g8_load1o(ra, a + 64, offa);
;   g8_load1o(rb, b + 64, offb);
;   for (int kb = 0; kb + 2 < nkb; ++kb) {
;     __syncthreads();
;     g8_store1(L + ((kb + 1) & 1) * 32768, ra, lrow, lch);
;     g8_load1o(ra, a + (kb + 2) * 64, offa);
;     __builtin_amdgcn_sched_barrier(0);
;     g8_compute<0, 1>(acc, L + (kb & 1) * 32768, wm, wn, lane);
;     __builtin_amdgcn_sched_barrier(0);
;     g8_store1(L + ((kb + 1) & 1) * 32768 + 16384, rb, lrow, lch);
;     g8_load1o(rb, b + (kb + 2) * 64, offb);
;     __builtin_amdgcn_sched_barrier(0);
;     g8_compute<1, 2>(acc, L + (kb & 1) * 32768, wm, wn, lane);
;   }
.Lstg_778_a:
	s_waitcnt vmcnt(5)
	ds_write_b128 v191, v[22:25]
	ds_write_b128 v191, v[18:21] offset:8192
	ds_write_b128 v191, v[26:29] offset:16384
	s_waitcnt vmcnt(4)
	ds_write_b128 v191, v[30:33] offset:24576
	s_add_u32 s54, s52, s0
	s_addc_u32 s55, s53, s1
	global_load_dwordx4 v[22:25], v187, s[54:55]
	global_load_dwordx4 v[26:29], v183, s[54:55]
	global_load_dwordx4 v[18:21], v185, s[54:55]
	global_load_dwordx4 v[30:33], v181, s[54:55]
	s_and_b32 s2, s2, 0x8000
	s_lshl_b32 s2, s2, 1
	v_lshl_add_u32 v202, v169, 1, s2
	v_add_u32_e32 v203, v202, v188
	ds_read_b128 v[192:195], v203
	ds_read_b128 v[198:201], v203 offset:2048
	ds_read_b128 v[206:209], v203 offset:4096
	ds_read_b128 v[210:213], v203 offset:6144
	ds_read_b128 v[214:217], v203 offset:8192
	ds_read_b128 v[218:221], v203 offset:10240
	ds_read_b128 v[222:225], v203 offset:12288
	ds_read_b128 v[226:229], v203 offset:14336
	v_add_u32_e32 v202, v202, v171
	ds_read_b128 v[230:233], v202 offset:32768
	ds_read_b128 v[234:237], v202 offset:34816
	ds_read_b128 v[238:241], v202 offset:36864
	ds_read_b128 v[242:245], v202 offset:38912
	s_waitcnt lgkmcnt(3)
	v_mfma_f32_16x16x32_bf16 v[158:161], v[230:233], v[192:195], v[158:161]
	s_waitcnt lgkmcnt(2)
	v_mfma_f32_16x16x32_bf16 v[154:157], v[234:237], v[192:195], v[154:157]
	s_waitcnt lgkmcnt(1)
	v_mfma_f32_16x16x32_bf16 v[150:153], v[238:241], v[192:195], v[150:153]
	s_waitcnt lgkmcnt(0)
	v_mfma_f32_16x16x32_bf16 v[146:149], v[242:245], v[192:195], v[146:149]
	v_mfma_f32_16x16x32_bf16 v[142:145], v[230:233], v[198:201], v[142:145]
	v_mfma_f32_16x16x32_bf16 v[138:141], v[234:237], v[198:201], v[138:141]
	v_mfma_f32_16x16x32_bf16 v[134:137], v[238:241], v[198:201], v[134:137]
	v_mfma_f32_16x16x32_bf16 v[130:133], v[242:245], v[198:201], v[130:133]
	v_mfma_f32_16x16x32_bf16 v[126:129], v[230:233], v[206:209], v[126:129]
	v_mfma_f32_16x16x32_bf16 v[122:125], v[234:237], v[206:209], v[122:125]
	v_mfma_f32_16x16x32_bf16 v[118:121], v[238:241], v[206:209], v[118:121]
	v_mfma_f32_16x16x32_bf16 v[114:117], v[242:245], v[206:209], v[114:117]
	v_mfma_f32_16x16x32_bf16 v[110:113], v[230:233], v[210:213], v[110:113]
	v_mfma_f32_16x16x32_bf16 v[106:109], v[234:237], v[210:213], v[106:109]
	v_mfma_f32_16x16x32_bf16 v[102:105], v[238:241], v[210:213], v[102:105]
	v_mfma_f32_16x16x32_bf16 v[98:101], v[242:245], v[210:213], v[98:101]
	v_mfma_f32_16x16x32_bf16 v[94:97], v[230:233], v[214:217], v[94:97]
	v_mfma_f32_16x16x32_bf16 v[90:93], v[234:237], v[214:217], v[90:93]
	v_mfma_f32_16x16x32_bf16 v[86:89], v[238:241], v[214:217], v[86:89]
	v_mfma_f32_16x16x32_bf16 v[82:85], v[242:245], v[214:217], v[82:85]
	v_mfma_f32_16x16x32_bf16 v[78:81], v[230:233], v[218:221], v[78:81]
	v_mfma_f32_16x16x32_bf16 v[74:77], v[234:237], v[218:221], v[74:77]
	v_mfma_f32_16x16x32_bf16 v[70:73], v[238:241], v[218:221], v[70:73]
	v_mfma_f32_16x16x32_bf16 v[66:69], v[242:245], v[218:221], v[66:69]
	v_mfma_f32_16x16x32_bf16 v[62:65], v[230:233], v[222:225], v[62:65]
	v_mfma_f32_16x16x32_bf16 v[58:61], v[234:237], v[222:225], v[58:61]
	v_mfma_f32_16x16x32_bf16 v[54:57], v[238:241], v[222:225], v[54:57]
	v_mfma_f32_16x16x32_bf16 v[50:53], v[242:245], v[222:225], v[50:53]
	v_mfma_f32_16x16x32_bf16 v[46:49], v[230:233], v[226:229], v[46:49]
	v_mfma_f32_16x16x32_bf16 v[42:45], v[234:237], v[226:229], v[42:45]
	v_mfma_f32_16x16x32_bf16 v[38:41], v[238:241], v[226:229], v[38:41]
	v_mfma_f32_16x16x32_bf16 v[34:37], v[242:245], v[226:229], v[34:37]
	s_waitcnt vmcnt(7)
	ds_write_b128 v191, v[14:17] offset:32768
	s_waitcnt vmcnt(6)
	ds_write_b128 v191, v[2:5] offset:40960
	s_waitcnt vmcnt(5)
	ds_write_b128 v191, v[6:9] offset:49152
	s_waitcnt vmcnt(4)
	ds_write_b128 v191, v[10:13] offset:57344
	s_add_u32 s58, s56, s0
	s_addc_u32 s59, s57, s1
	global_load_dwordx4 v[14:17], v179, s[58:59]
	global_load_dwordx4 v[2:5], v177, s[58:59]
	global_load_dwordx4 v[6:9], v175, s[58:59]
	global_load_dwordx4 v[10:13], v173, s[58:59]
	v_lshl_add_u32 v191, v189, 1, s2
	v_add_u32_e32 v202, v191, v188
	ds_read_b128 v[192:195], v202
	ds_read_b128 v[198:201], v202 offset:2048
	ds_read_b128 v[206:209], v202 offset:4096
	ds_read_b128 v[210:213], v202 offset:6144
	ds_read_b128 v[214:217], v202 offset:8192
	ds_read_b128 v[218:221], v202 offset:10240
	ds_read_b128 v[222:225], v202 offset:12288
	ds_read_b128 v[226:229], v202 offset:14336
	v_add_u32_e32 v191, v191, v171
	ds_read_b128 v[230:233], v191 offset:32768
	ds_read_b128 v[234:237], v191 offset:34816
	ds_read_b128 v[238:241], v191 offset:36864
	ds_read_b128 v[242:245], v191 offset:38912
	s_cmp_lg_u32 s101, 0
	s_cbranch_scc1 .Lstg_778_b
	s_waitcnt lgkmcnt(3)
	v_mfma_f32_16x16x32_bf16 v[158:161], v[230:233], v[192:195], v[158:161]
	s_waitcnt lgkmcnt(2)
	v_mfma_f32_16x16x32_bf16 v[154:157], v[234:237], v[192:195], v[154:157]
	s_waitcnt lgkmcnt(1)
	v_mfma_f32_16x16x32_bf16 v[150:153], v[238:241], v[192:195], v[150:153]
	s_waitcnt lgkmcnt(0)
	v_mfma_f32_16x16x32_bf16 v[146:149], v[242:245], v[192:195], v[146:149]
	v_mfma_f32_16x16x32_bf16 v[142:145], v[230:233], v[198:201], v[142:145]
	v_mfma_f32_16x16x32_bf16 v[138:141], v[234:237], v[198:201], v[138:141]
	v_mfma_f32_16x16x32_bf16 v[134:137], v[238:241], v[198:201], v[134:137]
	v_mfma_f32_16x16x32_bf16 v[130:133], v[242:245], v[198:201], v[130:133]
	v_mfma_f32_16x16x32_bf16 v[126:129], v[230:233], v[206:209], v[126:129]
	v_mfma_f32_16x16x32_bf16 v[122:125], v[234:237], v[206:209], v[122:125]
	v_mfma_f32_16x16x32_bf16 v[118:121], v[238:241], v[206:209], v[118:121]
	v_mfma_f32_16x16x32_bf16 v[114:117], v[242:245], v[206:209], v[114:117]
	v_mfma_f32_16x16x32_bf16 v[110:113], v[230:233], v[210:213], v[110:113]
	v_mfma_f32_16x16x32_bf16 v[106:109], v[234:237], v[210:213], v[106:109]
	v_mfma_f32_16x16x32_bf16 v[102:105], v[238:241], v[210:213], v[102:105]
	v_mfma_f32_16x16x32_bf16 v[98:101], v[242:245], v[210:213], v[98:101]
	v_mfma_f32_16x16x32_bf16 v[94:97], v[230:233], v[214:217], v[94:97]
	v_mfma_f32_16x16x32_bf16 v[90:93], v[234:237], v[214:217], v[90:93]
	v_mfma_f32_16x16x32_bf16 v[86:89], v[238:241], v[214:217], v[86:89]
	v_mfma_f32_16x16x32_bf16 v[82:85], v[242:245], v[214:217], v[82:85]
	v_mfma_f32_16x16x32_bf16 v[78:81], v[230:233], v[218:221], v[78:81]
	v_mfma_f32_16x16x32_bf16 v[74:77], v[234:237], v[218:221], v[74:77]
	v_mfma_f32_16x16x32_bf16 v[70:73], v[238:241], v[218:221], v[70:73]
	v_mfma_f32_16x16x32_bf16 v[66:69], v[242:245], v[218:221], v[66:69]
	v_mfma_f32_16x16x32_bf16 v[62:65], v[230:233], v[222:225], v[62:65]
	v_mfma_f32_16x16x32_bf16 v[58:61], v[234:237], v[222:225], v[58:61]
	v_mfma_f32_16x16x32_bf16 v[54:57], v[238:241], v[222:225], v[54:57]
	v_mfma_f32_16x16x32_bf16 v[50:53], v[242:245], v[222:225], v[50:53]
	v_mfma_f32_16x16x32_bf16 v[46:49], v[230:233], v[226:229], v[46:49]
	v_mfma_f32_16x16x32_bf16 v[42:45], v[234:237], v[226:229], v[42:45]
	v_mfma_f32_16x16x32_bf16 v[38:41], v[238:241], v[226:229], v[38:41]
	v_mfma_f32_16x16x32_bf16 v[34:37], v[242:245], v[226:229], v[34:37]

; #pragma unroll
;   for (int ks = KS0; ks < KS1; ++ks) {
;     bf16x8 af[8], bfr[4];
; #pragma unroll
;     for (int i = 0; i < 8; ++i) {
;       const int r = wm * 128 + i * 16 + (lane & 15);
;       af[i] = *(const bf16x8*)(S + r * 64 + (((ks * 4 + (lane >> 4)) ^ ((r >> 1) & 7)) << 3));
;     }
; #pragma unroll
;     for (int j = 0; j < 4; ++j) {
;       const int r = wn * 64 + j * 16 + (lane & 15);
;       bfr[j] = *(const bf16x8*)(S + 16384 + r * 64 + (((ks * 4 + (lane >> 4)) ^ ((r >> 1) & 7)) << 3));
;     }
;     __builtin_amdgcn_s_setprio(1);
; #pragma unroll
;     for (int i = 0; i < 8; ++i)
; #pragma unroll
;       for (int j = 0; j < 4; ++j) acc[i][j] = mfma16(bfr[j], af[i], acc[i][j]);
;     __builtin_amdgcn_s_setprio(0);
;   }
; }
; DI void g8_load1o(u32x4 (&r4)[4], const bf16_t* base, const unsigned (&off)[4]) {
; #pragma unroll
;   for (int i = 0; i < 4; ++i) r4[i] = *(const u32x4*)(base + off[i]);
; }
; DI void gemm8_accum(f32x4 (&acc)[8][4], const bf16_t* a, size_t lda, const bf16_t* b, size_t ldb, int nkb, bf16_t* L,
;                     const bool pre, const bf16_t* an, size_t ldan, const bf16_t* bn, size_t ldbn) {
;   const int tid = TID8(), lane = tid & 63, w = tid >> 6;
;   const int wm = w >> 2, wn = w & 3;
;   const int lrow = tid >> 3, lch = tid & 7;
;   u32x4 ra[4], rb[4];
;   unsigned offa[4], offb[4];
; #pragma unroll
;   for (int i = 0; i < 4; ++i) {
;     offa[i] = (unsigned)(lrow + 64 * i) * (unsigned)lda + (unsigned)(lch * 8);
;     offb[i] = (unsigned)(lrow + 64 * i) * (unsigned)ldb + (unsigned)(lch * 8);
;   }
;   if (!pre) {
;     g8_load1o(ra, a, offa);
;     g8_load1o(rb, b, offb);
;     __syncthreads();
;     g8_store(L, ra, rb, lrow, lch);
;   }
;   g8_load1o(ra, a + 64, offa);
;   g8_load1o(rb, b + 64, offb);
;   for (int kb = 0; kb + 2 < nkb; ++kb) {
;     __syncthreads();
;     g8_store1(L + ((kb + 1) & 1) * 32768, ra, lrow, lch);
;     g8_load1o(ra, a + (kb + 2) * 64, offa);
;     __builtin_amdgcn_sched_barrier(0);
;     g8_compute<0, 1>(acc, L + (kb & 1) * 32768, wm, wn, lane);
;     __builtin_amdgcn_sched_barrier(0);
;     g8_store1(L + ((kb + 1) & 1) * 32768 + 16384, rb, lrow, lch);
;     g8_load1o(rb, b + (kb + 2) * 64, offb);
;     __builtin_amdgcn_sched_barrier(0);
;     g8_compute<1, 2>(acc, L + (kb & 1) * 32768, wm, wn, lane);
;   }
.Lstg_780_a:
	s_waitcnt vmcnt(7)
	ds_write_b128 v193, v[146:149]
	s_waitcnt vmcnt(5)
	ds_write_b128 v193, v[150:153] offset:8192
	s_waitcnt vmcnt(4)
	ds_write_b128 v193, v[154:157] offset:16384
	s_waitcnt vmcnt(3)
	ds_write_b128 v193, v[158:161] offset:24576
	s_add_u32 s54, s52, s0
	s_addc_u32 s55, s53, s1
	global_load_dwordx4 v[146:149], v187, s[54:55]
	global_load_dwordx4 v[150:153], v185, s[54:55]
	global_load_dwordx4 v[154:157], v183, s[54:55]
	global_load_dwordx4 v[158:161], v181, s[54:55]
	s_and_b32 s2, s2, 0x8000
	s_lshl_b32 s2, s2, 1
	v_lshl_add_u32 v194, v192, 1, s2
	v_add_u32_e32 v195, v194, v189
	ds_read_b128 v[198:201], v195
	ds_read_b128 v[206:209], v195 offset:2048
	ds_read_b128 v[210:213], v195 offset:4096
	ds_read_b128 v[214:217], v195 offset:6144
	ds_read_b128 v[218:221], v195 offset:8192
	ds_read_b128 v[222:225], v195 offset:10240
	ds_read_b128 v[226:229], v195 offset:12288
	ds_read_b128 v[230:233], v195 offset:14336
	v_add_u32_e32 v194, v194, v188
	ds_read_b128 v[234:237], v194 offset:32768
	ds_read_b128 v[238:241], v194 offset:34816
	ds_read_b128 v[242:245], v194 offset:36864
	ds_read_b128 v[246:249], v194 offset:38912
	s_waitcnt lgkmcnt(3)
	v_mfma_f32_16x16x32_bf16 v[2:5], v[234:237], v[198:201], v[2:5]
	s_waitcnt lgkmcnt(2)
	v_mfma_f32_16x16x32_bf16 v[6:9], v[238:241], v[198:201], v[6:9]
	s_waitcnt lgkmcnt(1)
	v_mfma_f32_16x16x32_bf16 v[10:13], v[242:245], v[198:201], v[10:13]
	s_waitcnt lgkmcnt(0)
	v_mfma_f32_16x16x32_bf16 v[14:17], v[246:249], v[198:201], v[14:17]
	v_mfma_f32_16x16x32_bf16 v[22:25], v[234:237], v[206:209], v[22:25]
	v_mfma_f32_16x16x32_bf16 v[30:33], v[238:241], v[206:209], v[30:33]
	v_mfma_f32_16x16x32_bf16 v[38:41], v[242:245], v[206:209], v[38:41]
	v_mfma_f32_16x16x32_bf16 v[46:49], v[246:249], v[206:209], v[46:49]
	v_mfma_f32_16x16x32_bf16 v[54:57], v[234:237], v[210:213], v[54:57]
	v_mfma_f32_16x16x32_bf16 v[62:65], v[238:241], v[210:213], v[62:65]
	v_mfma_f32_16x16x32_bf16 v[70:73], v[242:245], v[210:213], v[70:73]
	v_mfma_f32_16x16x32_bf16 v[78:81], v[246:249], v[210:213], v[78:81]
	v_mfma_f32_16x16x32_bf16 v[86:89], v[234:237], v[214:217], v[86:89]
	v_mfma_f32_16x16x32_bf16 v[94:97], v[238:241], v[214:217], v[94:97]
	v_mfma_f32_16x16x32_bf16 v[102:105], v[242:245], v[214:217], v[102:105]
	v_mfma_f32_16x16x32_bf16 v[110:113], v[246:249], v[214:217], v[110:113]
	v_mfma_f32_16x16x32_bf16 v[118:121], v[234:237], v[218:221], v[118:121]
	v_mfma_f32_16x16x32_bf16 v[126:129], v[238:241], v[218:221], v[126:129]
	v_mfma_f32_16x16x32_bf16 v[122:125], v[242:245], v[218:221], v[122:125]
	v_mfma_f32_16x16x32_bf16 v[114:117], v[246:249], v[218:221], v[114:117]
	v_mfma_f32_16x16x32_bf16 v[106:109], v[234:237], v[222:225], v[106:109]
	v_mfma_f32_16x16x32_bf16 v[98:101], v[238:241], v[222:225], v[98:101]
	v_mfma_f32_16x16x32_bf16 v[90:93], v[242:245], v[222:225], v[90:93]
	v_mfma_f32_16x16x32_bf16 v[82:85], v[246:249], v[222:225], v[82:85]
	v_mfma_f32_16x16x32_bf16 v[74:77], v[234:237], v[226:229], v[74:77]
	v_mfma_f32_16x16x32_bf16 v[66:69], v[238:241], v[226:229], v[66:69]
	v_mfma_f32_16x16x32_bf16 v[58:61], v[242:245], v[226:229], v[58:61]
	v_mfma_f32_16x16x32_bf16 v[50:53], v[246:249], v[226:229], v[50:53]
	v_mfma_f32_16x16x32_bf16 v[42:45], v[234:237], v[230:233], v[42:45]
	v_mfma_f32_16x16x32_bf16 v[34:37], v[238:241], v[230:233], v[34:37]
	v_mfma_f32_16x16x32_bf16 v[26:29], v[242:245], v[230:233], v[26:29]
	v_mfma_f32_16x16x32_bf16 v[18:21], v[246:249], v[230:233], v[18:21]
	s_waitcnt vmcnt(6)
	ds_write_b128 v193, v[130:133] offset:32768
	s_waitcnt vmcnt(5)
	ds_write_b128 v193, v[138:141] offset:40960
	s_waitcnt vmcnt(4)
	ds_write_b128 v193, v[134:137] offset:49152
	ds_write_b128 v193, v[142:145] offset:57344
	s_add_u32 s58, s56, s0
	s_addc_u32 s59, s57, s1
	global_load_dwordx4 v[130:133], v179, s[58:59]
	global_load_dwordx4 v[138:141], v177, s[58:59]
	global_load_dwordx4 v[134:137], v175, s[58:59]
	global_load_dwordx4 v[142:145], v173, s[58:59]
	v_lshl_add_u32 v193, v190, 1, s2
	v_add_u32_e32 v194, v193, v189
	ds_read_b128 v[198:201], v194
	ds_read_b128 v[206:209], v194 offset:2048
	ds_read_b128 v[210:213], v194 offset:4096
	ds_read_b128 v[214:217], v194 offset:6144
	ds_read_b128 v[218:221], v194 offset:8192
	ds_read_b128 v[222:225], v194 offset:10240
	ds_read_b128 v[226:229], v194 offset:12288
	ds_read_b128 v[230:233], v194 offset:14336
	v_add_u32_e32 v193, v193, v188
	ds_read_b128 v[234:237], v193 offset:32768
	ds_read_b128 v[238:241], v193 offset:34816
	ds_read_b128 v[242:245], v193 offset:36864
	ds_read_b128 v[246:249], v193 offset:38912
	s_cmp_lg_u32 s101, 0
	s_cbranch_scc1 .Lstg_780_b
	s_waitcnt lgkmcnt(3)
	v_mfma_f32_16x16x32_bf16 v[2:5], v[234:237], v[198:201], v[2:5]
	s_waitcnt lgkmcnt(2)
	v_mfma_f32_16x16x32_bf16 v[6:9], v[238:241], v[198:201], v[6:9]
	s_waitcnt lgkmcnt(1)
	v_mfma_f32_16x16x32_bf16 v[10:13], v[242:245], v[198:201], v[10:13]
	s_waitcnt lgkmcnt(0)
	v_mfma_f32_16x16x32_bf16 v[14:17], v[246:249], v[198:201], v[14:17]
	v_mfma_f32_16x16x32_bf16 v[22:25], v[234:237], v[206:209], v[22:25]
	v_mfma_f32_16x16x32_bf16 v[30:33], v[238:241], v[206:209], v[30:33]
	v_mfma_f32_16x16x32_bf16 v[38:41], v[242:245], v[206:209], v[38:41]
	v_mfma_f32_16x16x32_bf16 v[46:49], v[246:249], v[206:209], v[46:49]
	v_mfma_f32_16x16x32_bf16 v[54:57], v[234:237], v[210:213], v[54:57]
	v_mfma_f32_16x16x32_bf16 v[62:65], v[238:241], v[210:213], v[62:65]
	v_mfma_f32_16x16x32_bf16 v[70:73], v[242:245], v[210:213], v[70:73]
	v_mfma_f32_16x16x32_bf16 v[78:81], v[246:249], v[210:213], v[78:81]
	v_mfma_f32_16x16x32_bf16 v[86:89], v[234:237], v[214:217], v[86:89]
	v_mfma_f32_16x16x32_bf16 v[94:97], v[238:241], v[214:217], v[94:97]
	v_mfma_f32_16x16x32_bf16 v[102:105], v[242:245], v[214:217], v[102:105]
	v_mfma_f32_16x16x32_bf16 v[110:113], v[246:249], v[214:217], v[110:113]
	v_mfma_f32_16x16x32_bf16 v[118:121], v[234:237], v[218:221], v[118:121]
	v_mfma_f32_16x16x32_bf16 v[126:129], v[238:241], v[218:221], v[126:129]
	v_mfma_f32_16x16x32_bf16 v[122:125], v[242:245], v[218:221], v[122:125]
	v_mfma_f32_16x16x32_bf16 v[114:117], v[246:249], v[218:221], v[114:117]
	v_mfma_f32_16x16x32_bf16 v[106:109], v[234:237], v[222:225], v[106:109]
	v_mfma_f32_16x16x32_bf16 v[98:101], v[238:241], v[222:225], v[98:101]
	v_mfma_f32_16x16x32_bf16 v[90:93], v[242:245], v[222:225], v[90:93]
	v_mfma_f32_16x16x32_bf16 v[82:85], v[246:249], v[222:225], v[82:85]
	v_mfma_f32_16x16x32_bf16 v[74:77], v[234:237], v[226:229], v[74:77]
	v_mfma_f32_16x16x32_bf16 v[66:69], v[238:241], v[226:229], v[66:69]
	v_mfma_f32_16x16x32_bf16 v[58:61], v[242:245], v[226:229], v[58:61]
	v_mfma_f32_16x16x32_bf16 v[50:53], v[246:249], v[226:229], v[50:53]
	v_mfma_f32_16x16x32_bf16 v[42:45], v[234:237], v[230:233], v[42:45]
	v_mfma_f32_16x16x32_bf16 v[34:37], v[238:241], v[230:233], v[34:37]
	v_mfma_f32_16x16x32_bf16 v[26:29], v[242:245], v[230:233], v[26:29]
	v_mfma_f32_16x16x32_bf16 v[18:21], v[246:249], v[230:233], v[18:21]

; #pragma unroll
;   for (int ks = KS0; ks < KS1; ++ks) {
;     bf16x8 af[8], bfr[4];
; #pragma unroll
;     for (int i = 0; i < 8; ++i) {
;       const int r = wm * 128 + i * 16 + (lane & 15);
;       af[i] = *(const bf16x8*)(S + r * 64 + (((ks * 4 + (lane >> 4)) ^ ((r >> 1) & 7)) << 3));
;     }
; #pragma unroll
;     for (int j = 0; j < 4; ++j) {
;       const int r = wn * 64 + j * 16 + (lane & 15);
;       bfr[j] = *(const bf16x8*)(S + 16384 + r * 64 + (((ks * 4 + (lane >> 4)) ^ ((r >> 1) & 7)) << 3));
;     }
;     __builtin_amdgcn_s_setprio(1);
; #pragma unroll
;     for (int i = 0; i < 8; ++i)
; #pragma unroll
;       for (int j = 0; j < 4; ++j) acc[i][j] = mfma16(bfr[j], af[i], acc[i][j]);
;     __builtin_amdgcn_s_setprio(0);
;   }
; }
; DI void g8_load1o(u32x4 (&r4)[4], const bf16_t* base, const unsigned (&off)[4]) {
; #pragma unroll
;   for (int i = 0; i < 4; ++i) r4[i] = *(const u32x4*)(base + off[i]);
; }
; DI void gemm8_accum(f32x4 (&acc)[8][4], const bf16_t* a, size_t lda, const bf16_t* b, size_t ldb, int nkb, bf16_t* L,
;                     const bool pre, const bf16_t* an, size_t ldan, const bf16_t* bn, size_t ldbn) {
;   const int tid = TID8(), lane = tid & 63, w = tid >> 6;
;   const int wm = w >> 2, wn = w & 3;
;   const int lrow = tid >> 3, lch = tid & 7;
;   u32x4 ra[4], rb[4];
;   unsigned offa[4], offb[4];
; #pragma unroll
;   for (int i = 0; i < 4; ++i) {
;     offa[i] = (unsigned)(lrow + 64 * i) * (unsigned)lda + (unsigned)(lch * 8);
;     offb[i] = (unsigned)(lrow + 64 * i) * (unsigned)ldb + (unsigned)(lch * 8);
;   }
;   if (!pre) {
;     g8_load1o(ra, a, offa);
;     g8_load1o(rb, b, offb);
;     __syncthreads();
;     g8_store(L, ra, rb, lrow, lch);
;   }
;   g8_load1o(ra, a + 64, offa);
;   g8_load1o(rb, b + 64, offb);
;   for (int kb = 0; kb + 2 < nkb; ++kb) {
;     __syncthreads();
;     g8_store1(L + ((kb + 1) & 1) * 32768, ra, lrow, lch);
;     g8_load1o(ra, a + (kb + 2) * 64, offa);
;     __builtin_amdgcn_sched_barrier(0);
;     g8_compute<0, 1>(acc, L + (kb & 1) * 32768, wm, wn, lane);
;     __builtin_amdgcn_sched_barrier(0);
;     g8_store1(L + ((kb + 1) & 1) * 32768 + 16384, rb, lrow, lch);
;     g8_load1o(rb, b + (kb + 2) * 64, offb);
;     __builtin_amdgcn_sched_barrier(0);
;     g8_compute<1, 2>(acc, L + (kb & 1) * 32768, wm, wn, lane);
;   }
.Lstg_830_a:
	s_waitcnt vmcnt(7)
	ds_write_b128 v171, v[18:21]
	s_waitcnt vmcnt(6)
	ds_write_b128 v171, v[22:25] offset:8192
	s_waitcnt vmcnt(5)
	ds_write_b128 v171, v[26:29] offset:16384
	s_waitcnt vmcnt(4)
	ds_write_b128 v171, v[30:33] offset:24576
	s_add_u32 s54, s52, s0
	s_addc_u32 s55, s53, s1
	global_load_dwordx4 v[18:21], v193, s[54:55]
	global_load_dwordx4 v[22:25], v191, s[54:55]
	global_load_dwordx4 v[26:29], v189, s[54:55]
	global_load_dwordx4 v[30:33], v187, s[54:55]
	s_and_b32 s2, s2, 0x8000
	s_lshl_b32 s2, s2, 1
	v_lshl_add_u32 v173, v169, 1, s2
	v_add_u32_e32 v175, v173, v195
	ds_read_b128 v[198:201], v175
	ds_read_b128 v[206:209], v175 offset:2048
	ds_read_b128 v[210:213], v175 offset:4096
	ds_read_b128 v[214:217], v175 offset:6144
	ds_read_b128 v[218:221], v175 offset:8192
	ds_read_b128 v[222:225], v175 offset:10240
	ds_read_b128 v[226:229], v175 offset:12288
	ds_read_b128 v[230:233], v175 offset:14336
	v_add_u32_e32 v173, v173, v194
	ds_read_b128 v[234:237], v173 offset:32768
	ds_read_b128 v[238:241], v173 offset:34816
	ds_read_b128 v[242:245], v173 offset:36864
	ds_read_b128 v[246:249], v173 offset:38912
	s_waitcnt lgkmcnt(3)
	v_mfma_f32_16x16x32_bf16 v[158:161], v[234:237], v[198:201], v[158:161]
	s_waitcnt lgkmcnt(2)
	v_mfma_f32_16x16x32_bf16 v[154:157], v[238:241], v[198:201], v[154:157]
	s_waitcnt lgkmcnt(1)
	v_mfma_f32_16x16x32_bf16 v[150:153], v[242:245], v[198:201], v[150:153]
	s_waitcnt lgkmcnt(0)
	v_mfma_f32_16x16x32_bf16 v[146:149], v[246:249], v[198:201], v[146:149]
	v_mfma_f32_16x16x32_bf16 v[142:145], v[234:237], v[206:209], v[142:145]
	v_mfma_f32_16x16x32_bf16 v[138:141], v[238:241], v[206:209], v[138:141]
	v_mfma_f32_16x16x32_bf16 v[134:137], v[242:245], v[206:209], v[134:137]
	v_mfma_f32_16x16x32_bf16 v[130:133], v[246:249], v[206:209], v[130:133]
	v_mfma_f32_16x16x32_bf16 v[126:129], v[234:237], v[210:213], v[126:129]
	v_mfma_f32_16x16x32_bf16 v[122:125], v[238:241], v[210:213], v[122:125]
	v_mfma_f32_16x16x32_bf16 v[118:121], v[242:245], v[210:213], v[118:121]
	v_mfma_f32_16x16x32_bf16 v[114:117], v[246:249], v[210:213], v[114:117]
	v_mfma_f32_16x16x32_bf16 v[110:113], v[234:237], v[214:217], v[110:113]
	v_mfma_f32_16x16x32_bf16 v[106:109], v[238:241], v[214:217], v[106:109]
	v_mfma_f32_16x16x32_bf16 v[102:105], v[242:245], v[214:217], v[102:105]
	v_mfma_f32_16x16x32_bf16 v[98:101], v[246:249], v[214:217], v[98:101]
	v_mfma_f32_16x16x32_bf16 v[94:97], v[234:237], v[218:221], v[94:97]
	v_mfma_f32_16x16x32_bf16 v[90:93], v[238:241], v[218:221], v[90:93]
	v_mfma_f32_16x16x32_bf16 v[86:89], v[242:245], v[218:221], v[86:89]
	v_mfma_f32_16x16x32_bf16 v[82:85], v[246:249], v[218:221], v[82:85]
	v_mfma_f32_16x16x32_bf16 v[78:81], v[234:237], v[222:225], v[78:81]
	v_mfma_f32_16x16x32_bf16 v[74:77], v[238:241], v[222:225], v[74:77]
	v_mfma_f32_16x16x32_bf16 v[70:73], v[242:245], v[222:225], v[70:73]
	v_mfma_f32_16x16x32_bf16 v[66:69], v[246:249], v[222:225], v[66:69]
	v_mfma_f32_16x16x32_bf16 v[62:65], v[234:237], v[226:229], v[62:65]
	v_mfma_f32_16x16x32_bf16 v[58:61], v[238:241], v[226:229], v[58:61]
	v_mfma_f32_16x16x32_bf16 v[54:57], v[242:245], v[226:229], v[54:57]
	v_mfma_f32_16x16x32_bf16 v[50:53], v[246:249], v[226:229], v[50:53]
	v_mfma_f32_16x16x32_bf16 v[46:49], v[234:237], v[230:233], v[46:49]
	v_mfma_f32_16x16x32_bf16 v[42:45], v[238:241], v[230:233], v[42:45]
	v_mfma_f32_16x16x32_bf16 v[38:41], v[242:245], v[230:233], v[38:41]
	v_mfma_f32_16x16x32_bf16 v[34:37], v[246:249], v[230:233], v[34:37]
	s_waitcnt vmcnt(7)
	ds_write_b128 v171, v[14:17] offset:32768
	s_waitcnt vmcnt(6)
	ds_write_b128 v171, v[2:5] offset:40960
	s_waitcnt vmcnt(5)
	ds_write_b128 v171, v[6:9] offset:49152
	s_waitcnt vmcnt(4)
	ds_write_b128 v171, v[10:13] offset:57344
	s_add_u32 s58, s56, s0
	s_addc_u32 s59, s57, s1
	global_load_dwordx4 v[14:17], v185, s[58:59]
	global_load_dwordx4 v[2:5], v183, s[58:59]
	global_load_dwordx4 v[6:9], v181, s[58:59]
	global_load_dwordx4 v[10:13], v179, s[58:59]
	v_lshl_add_u32 v171, v205, 1, s2
	v_add_u32_e32 v173, v171, v195
	ds_read_b128 v[198:201], v173
	ds_read_b128 v[206:209], v173 offset:2048
	ds_read_b128 v[210:213], v173 offset:4096
	ds_read_b128 v[214:217], v173 offset:6144
	ds_read_b128 v[218:221], v173 offset:8192
	ds_read_b128 v[222:225], v173 offset:10240
	ds_read_b128 v[226:229], v173 offset:12288
	ds_read_b128 v[230:233], v173 offset:14336
	v_add_u32_e32 v171, v171, v194
	ds_read_b128 v[234:237], v171 offset:32768
	ds_read_b128 v[238:241], v171 offset:34816
	ds_read_b128 v[242:245], v171 offset:36864
	ds_read_b128 v[246:249], v171 offset:38912
	s_cmp_lg_u32 s101, 0
	s_cbranch_scc1 .Lstg_830_b
	s_waitcnt lgkmcnt(3)
	v_mfma_f32_16x16x32_bf16 v[158:161], v[234:237], v[198:201], v[158:161]
	s_waitcnt lgkmcnt(2)
	v_mfma_f32_16x16x32_bf16 v[154:157], v[238:241], v[198:201], v[154:157]
	s_waitcnt lgkmcnt(1)
	v_mfma_f32_16x16x32_bf16 v[150:153], v[242:245], v[198:201], v[150:153]
	s_waitcnt lgkmcnt(0)
	v_mfma_f32_16x16x32_bf16 v[146:149], v[246:249], v[198:201], v[146:149]
	v_mfma_f32_16x16x32_bf16 v[142:145], v[234:237], v[206:209], v[142:145]
	v_mfma_f32_16x16x32_bf16 v[138:141], v[238:241], v[206:209], v[138:141]
	v_mfma_f32_16x16x32_bf16 v[134:137], v[242:245], v[206:209], v[134:137]
	v_mfma_f32_16x16x32_bf16 v[130:133], v[246:249], v[206:209], v[130:133]
	v_mfma_f32_16x16x32_bf16 v[126:129], v[234:237], v[210:213], v[126:129]
	v_mfma_f32_16x16x32_bf16 v[122:125], v[238:241], v[210:213], v[122:125]
	v_mfma_f32_16x16x32_bf16 v[118:121], v[242:245], v[210:213], v[118:121]
	v_mfma_f32_16x16x32_bf16 v[114:117], v[246:249], v[210:213], v[114:117]
	v_mfma_f32_16x16x32_bf16 v[110:113], v[234:237], v[214:217], v[110:113]
	v_mfma_f32_16x16x32_bf16 v[106:109], v[238:241], v[214:217], v[106:109]
	v_mfma_f32_16x16x32_bf16 v[102:105], v[242:245], v[214:217], v[102:105]
	v_mfma_f32_16x16x32_bf16 v[98:101], v[246:249], v[214:217], v[98:101]
	v_mfma_f32_16x16x32_bf16 v[94:97], v[234:237], v[218:221], v[94:97]
	v_mfma_f32_16x16x32_bf16 v[90:93], v[238:241], v[218:221], v[90:93]
	v_mfma_f32_16x16x32_bf16 v[86:89], v[242:245], v[218:221], v[86:89]
	v_mfma_f32_16x16x32_bf16 v[82:85], v[246:249], v[218:221], v[82:85]
	v_mfma_f32_16x16x32_bf16 v[78:81], v[234:237], v[222:225], v[78:81]
	v_mfma_f32_16x16x32_bf16 v[74:77], v[238:241], v[222:225], v[74:77]
	v_mfma_f32_16x16x32_bf16 v[70:73], v[242:245], v[222:225], v[70:73]
	v_mfma_f32_16x16x32_bf16 v[66:69], v[246:249], v[222:225], v[66:69]
	v_mfma_f32_16x16x32_bf16 v[62:65], v[234:237], v[226:229], v[62:65]
	v_mfma_f32_16x16x32_bf16 v[58:61], v[238:241], v[226:229], v[58:61]
	v_mfma_f32_16x16x32_bf16 v[54:57], v[242:245], v[226:229], v[54:57]
	v_mfma_f32_16x16x32_bf16 v[50:53], v[246:249], v[226:229], v[50:53]
	v_mfma_f32_16x16x32_bf16 v[46:49], v[234:237], v[230:233], v[46:49]
	v_mfma_f32_16x16x32_bf16 v[42:45], v[238:241], v[230:233], v[42:45]
	v_mfma_f32_16x16x32_bf16 v[38:41], v[242:245], v[230:233], v[38:41]
	v_mfma_f32_16x16x32_bf16 v[34:37], v[246:249], v[230:233], v[34:37]

; #pragma unroll
;   for (int ks = KS0; ks < KS1; ++ks) {
;     bf16x8 af[8], bfr[4];
; #pragma unroll
;     for (int i = 0; i < 8; ++i) {
;       const int r = wm * 128 + i * 16 + (lane & 15);
;       af[i] = *(const bf16x8*)(S + r * 64 + (((ks * 4 + (lane >> 4)) ^ ((r >> 1) & 7)) << 3));
;     }
; #pragma unroll
;     for (int j = 0; j < 4; ++j) {
;       const int r = wn * 64 + j * 16 + (lane & 15);
;       bfr[j] = *(const bf16x8*)(S + 16384 + r * 64 + (((ks * 4 + (lane >> 4)) ^ ((r >> 1) & 7)) << 3));
;     }
;     __builtin_amdgcn_s_setprio(1);
; #pragma unroll
;     for (int i = 0; i < 8; ++i)
; #pragma unroll
;       for (int j = 0; j < 4; ++j) acc[i][j] = mfma16(bfr[j], af[i], acc[i][j]);
;     __builtin_amdgcn_s_setprio(0);
;   }
; }
; DI void g8_load1o(u32x4 (&r4)[4], const bf16_t* base, const unsigned (&off)[4]) {
; #pragma unroll
;   for (int i = 0; i < 4; ++i) r4[i] = *(const u32x4*)(base + off[i]);
; }
; DI void gemm8_accum(f32x4 (&acc)[8][4], const bf16_t* a, size_t lda, const bf16_t* b, size_t ldb, int nkb, bf16_t* L,
;                     const bool pre, const bf16_t* an, size_t ldan, const bf16_t* bn, size_t ldbn) {
;   const int tid = TID8(), lane = tid & 63, w = tid >> 6;
;   const int wm = w >> 2, wn = w & 3;
;   const int lrow = tid >> 3, lch = tid & 7;
;   u32x4 ra[4], rb[4];
;   unsigned offa[4], offb[4];
; #pragma unroll
;   for (int i = 0; i < 4; ++i) {
;     offa[i] = (unsigned)(lrow + 64 * i) * (unsigned)lda + (unsigned)(lch * 8);
;     offb[i] = (unsigned)(lrow + 64 * i) * (unsigned)ldb + (unsigned)(lch * 8);
;   }
;   if (!pre) {
;     g8_load1o(ra, a, offa);
;     g8_load1o(rb, b, offb);
;     __syncthreads();
;     g8_store(L, ra, rb, lrow, lch);
;   }
;   g8_load1o(ra, a + 64, offa);
;   g8_load1o(rb, b + 64, offb);
;   for (int kb = 0; kb + 2 < nkb; ++kb) {
;     __syncthreads();
;     g8_store1(L + ((kb + 1) & 1) * 32768, ra, lrow, lch);
;     g8_load1o(ra, a + (kb + 2) * 64, offa);
;     __builtin_amdgcn_sched_barrier(0);
;     g8_compute<0, 1>(acc, L + (kb & 1) * 32768, wm, wn, lane);
;     __builtin_amdgcn_sched_barrier(0);
;     g8_store1(L + ((kb + 1) & 1) * 32768 + 16384, rb, lrow, lch);
;     g8_load1o(rb, b + (kb + 2) * 64, offb);
;     __builtin_amdgcn_sched_barrier(0);
;     g8_compute<1, 2>(acc, L + (kb & 1) * 32768, wm, wn, lane);
;   }
.Lstg_892_a:
	s_waitcnt vmcnt(5)
	ds_write_b128 v167, v[22:25]
	ds_write_b128 v167, v[18:21] offset:8192
	ds_write_b128 v167, v[26:29] offset:16384
	s_waitcnt vmcnt(4)
	ds_write_b128 v167, v[30:33] offset:24576
	s_add_u32 s54, s52, s0
	s_addc_u32 s55, s53, s1
	global_load_dwordx4 v[22:25], v185, s[54:55]
	global_load_dwordx4 v[26:29], v181, s[54:55]
	global_load_dwordx4 v[18:21], v183, s[54:55]
	global_load_dwordx4 v[30:33], v179, s[54:55]
	s_and_b32 s2, s2, 0x8000
	s_lshl_b32 s2, s2, 1
	v_lshl_add_u32 v169, v191, 1, s2
	v_add_u32_e32 v202, v169, v187
	ds_read_b128 v[192:195], v202
	ds_read_b128 v[198:201], v202 offset:2048
	ds_read_b128 v[206:209], v202 offset:4096
	ds_read_b128 v[210:213], v202 offset:6144
	ds_read_b128 v[214:217], v202 offset:8192
	ds_read_b128 v[218:221], v202 offset:10240
	ds_read_b128 v[222:225], v202 offset:12288
	ds_read_b128 v[226:229], v202 offset:14336
	v_add_u32_e32 v169, v169, v186
	ds_read_b128 v[230:233], v169 offset:32768
	ds_read_b128 v[234:237], v169 offset:34816
	ds_read_b128 v[238:241], v169 offset:36864
	ds_read_b128 v[242:245], v169 offset:38912
	s_waitcnt lgkmcnt(3)
	v_mfma_f32_16x16x32_bf16 v[158:161], v[230:233], v[192:195], v[158:161]
	s_waitcnt lgkmcnt(2)
	v_mfma_f32_16x16x32_bf16 v[154:157], v[234:237], v[192:195], v[154:157]
	s_waitcnt lgkmcnt(1)
	v_mfma_f32_16x16x32_bf16 v[150:153], v[238:241], v[192:195], v[150:153]
	s_waitcnt lgkmcnt(0)
	v_mfma_f32_16x16x32_bf16 v[146:149], v[242:245], v[192:195], v[146:149]
	v_mfma_f32_16x16x32_bf16 v[142:145], v[230:233], v[198:201], v[142:145]
	v_mfma_f32_16x16x32_bf16 v[138:141], v[234:237], v[198:201], v[138:141]
	v_mfma_f32_16x16x32_bf16 v[134:137], v[238:241], v[198:201], v[134:137]
	v_mfma_f32_16x16x32_bf16 v[130:133], v[242:245], v[198:201], v[130:133]
	v_mfma_f32_16x16x32_bf16 v[126:129], v[230:233], v[206:209], v[126:129]
	v_mfma_f32_16x16x32_bf16 v[122:125], v[234:237], v[206:209], v[122:125]
	v_mfma_f32_16x16x32_bf16 v[118:121], v[238:241], v[206:209], v[118:121]
	v_mfma_f32_16x16x32_bf16 v[114:117], v[242:245], v[206:209], v[114:117]
	v_mfma_f32_16x16x32_bf16 v[110:113], v[230:233], v[210:213], v[110:113]
	v_mfma_f32_16x16x32_bf16 v[106:109], v[234:237], v[210:213], v[106:109]
	v_mfma_f32_16x16x32_bf16 v[102:105], v[238:241], v[210:213], v[102:105]
	v_mfma_f32_16x16x32_bf16 v[98:101], v[242:245], v[210:213], v[98:101]
	v_mfma_f32_16x16x32_bf16 v[94:97], v[230:233], v[214:217], v[94:97]
	v_mfma_f32_16x16x32_bf16 v[90:93], v[234:237], v[214:217], v[90:93]
	v_mfma_f32_16x16x32_bf16 v[86:89], v[238:241], v[214:217], v[86:89]
	v_mfma_f32_16x16x32_bf16 v[82:85], v[242:245], v[214:217], v[82:85]
	v_mfma_f32_16x16x32_bf16 v[78:81], v[230:233], v[218:221], v[78:81]
	v_mfma_f32_16x16x32_bf16 v[74:77], v[234:237], v[218:221], v[74:77]
	v_mfma_f32_16x16x32_bf16 v[70:73], v[238:241], v[218:221], v[70:73]
	v_mfma_f32_16x16x32_bf16 v[66:69], v[242:245], v[218:221], v[66:69]
	v_mfma_f32_16x16x32_bf16 v[62:65], v[230:233], v[222:225], v[62:65]
	v_mfma_f32_16x16x32_bf16 v[58:61], v[234:237], v[222:225], v[58:61]
	v_mfma_f32_16x16x32_bf16 v[54:57], v[238:241], v[222:225], v[54:57]
	v_mfma_f32_16x16x32_bf16 v[50:53], v[242:245], v[222:225], v[50:53]
	v_mfma_f32_16x16x32_bf16 v[46:49], v[230:233], v[226:229], v[46:49]
	v_mfma_f32_16x16x32_bf16 v[42:45], v[234:237], v[226:229], v[42:45]
	v_mfma_f32_16x16x32_bf16 v[38:41], v[238:241], v[226:229], v[38:41]
	v_mfma_f32_16x16x32_bf16 v[34:37], v[242:245], v[226:229], v[34:37]
	s_waitcnt vmcnt(7)
	ds_write_b128 v167, v[14:17] offset:32768
	s_waitcnt vmcnt(6)
	ds_write_b128 v167, v[2:5] offset:40960
	s_waitcnt vmcnt(5)
	ds_write_b128 v167, v[6:9] offset:49152
	s_waitcnt vmcnt(4)
	ds_write_b128 v167, v[10:13] offset:57344
	s_add_u32 s58, s56, s0
	s_addc_u32 s59, s57, s1
	global_load_dwordx4 v[14:17], v177, s[58:59]
	global_load_dwordx4 v[2:5], v175, s[58:59]
	global_load_dwordx4 v[6:9], v173, s[58:59]
	global_load_dwordx4 v[10:13], v171, s[58:59]
	v_lshl_add_u32 v167, v188, 1, s2
	v_add_u32_e32 v169, v167, v187
	ds_read_b128 v[192:195], v169
	ds_read_b128 v[198:201], v169 offset:2048
	ds_read_b128 v[206:209], v169 offset:4096
	ds_read_b128 v[210:213], v169 offset:6144
	ds_read_b128 v[214:217], v169 offset:8192
	ds_read_b128 v[218:221], v169 offset:10240
	ds_read_b128 v[222:225], v169 offset:12288
	ds_read_b128 v[226:229], v169 offset:14336
	v_add_u32_e32 v167, v167, v186
	ds_read_b128 v[230:233], v167 offset:32768
	ds_read_b128 v[234:237], v167 offset:34816
	ds_read_b128 v[238:241], v167 offset:36864
	ds_read_b128 v[242:245], v167 offset:38912
	s_cmp_lg_u32 s101, 0
	s_cbranch_scc1 .Lstg_892_b
	s_waitcnt lgkmcnt(3)
	v_mfma_f32_16x16x32_bf16 v[158:161], v[230:233], v[192:195], v[158:161]
	s_waitcnt lgkmcnt(2)
	v_mfma_f32_16x16x32_bf16 v[154:157], v[234:237], v[192:195], v[154:157]
	s_waitcnt lgkmcnt(1)
	v_mfma_f32_16x16x32_bf16 v[150:153], v[238:241], v[192:195], v[150:153]
	s_waitcnt lgkmcnt(0)
	v_mfma_f32_16x16x32_bf16 v[146:149], v[242:245], v[192:195], v[146:149]
	v_mfma_f32_16x16x32_bf16 v[142:145], v[230:233], v[198:201], v[142:145]
	v_mfma_f32_16x16x32_bf16 v[138:141], v[234:237], v[198:201], v[138:141]
	v_mfma_f32_16x16x32_bf16 v[134:137], v[238:241], v[198:201], v[134:137]
	v_mfma_f32_16x16x32_bf16 v[130:133], v[242:245], v[198:201], v[130:133]
	v_mfma_f32_16x16x32_bf16 v[126:129], v[230:233], v[206:209], v[126:129]
	v_mfma_f32_16x16x32_bf16 v[122:125], v[234:237], v[206:209], v[122:125]
	v_mfma_f32_16x16x32_bf16 v[118:121], v[238:241], v[206:209], v[118:121]
	v_mfma_f32_16x16x32_bf16 v[114:117], v[242:245], v[206:209], v[114:117]
	v_mfma_f32_16x16x32_bf16 v[110:113], v[230:233], v[210:213], v[110:113]
	v_mfma_f32_16x16x32_bf16 v[106:109], v[234:237], v[210:213], v[106:109]
	v_mfma_f32_16x16x32_bf16 v[102:105], v[238:241], v[210:213], v[102:105]
	v_mfma_f32_16x16x32_bf16 v[98:101], v[242:245], v[210:213], v[98:101]
	v_mfma_f32_16x16x32_bf16 v[94:97], v[230:233], v[214:217], v[94:97]
	v_mfma_f32_16x16x32_bf16 v[90:93], v[234:237], v[214:217], v[90:93]
	v_mfma_f32_16x16x32_bf16 v[86:89], v[238:241], v[214:217], v[86:89]
	v_mfma_f32_16x16x32_bf16 v[82:85], v[242:245], v[214:217], v[82:85]
	v_mfma_f32_16x16x32_bf16 v[78:81], v[230:233], v[218:221], v[78:81]
	v_mfma_f32_16x16x32_bf16 v[74:77], v[234:237], v[218:221], v[74:77]
	v_mfma_f32_16x16x32_bf16 v[70:73], v[238:241], v[218:221], v[70:73]
	v_mfma_f32_16x16x32_bf16 v[66:69], v[242:245], v[218:221], v[66:69]
	v_mfma_f32_16x16x32_bf16 v[62:65], v[230:233], v[222:225], v[62:65]
	v_mfma_f32_16x16x32_bf16 v[58:61], v[234:237], v[222:225], v[58:61]
	v_mfma_f32_16x16x32_bf16 v[54:57], v[238:241], v[222:225], v[54:57]
	v_mfma_f32_16x16x32_bf16 v[50:53], v[242:245], v[222:225], v[50:53]
	v_mfma_f32_16x16x32_bf16 v[46:49], v[230:233], v[226:229], v[46:49]
	v_mfma_f32_16x16x32_bf16 v[42:45], v[234:237], v[226:229], v[42:45]
	v_mfma_f32_16x16x32_bf16 v[38:41], v[238:241], v[226:229], v[38:41]
	v_mfma_f32_16x16x32_bf16 v[34:37], v[242:245], v[226:229], v[34:37]

; #pragma unroll
;   for (int ks = KS0; ks < KS1; ++ks) {
;     bf16x8 af[8], bfr[4];
; #pragma unroll
;     for (int i = 0; i < 8; ++i) {
;       const int r = wm * 128 + i * 16 + (lane & 15);
;       af[i] = *(const bf16x8*)(S + r * 64 + (((ks * 4 + (lane >> 4)) ^ ((r >> 1) & 7)) << 3));
;     }
; #pragma unroll
;     for (int j = 0; j < 4; ++j) {
;       const int r = wn * 64 + j * 16 + (lane & 15);
;       bfr[j] = *(const bf16x8*)(S + 16384 + r * 64 + (((ks * 4 + (lane >> 4)) ^ ((r >> 1) & 7)) << 3));
;     }
;     __builtin_amdgcn_s_setprio(1);
; #pragma unroll
;     for (int i = 0; i < 8; ++i)
; #pragma unroll
;       for (int j = 0; j < 4; ++j) acc[i][j] = mfma16(bfr[j], af[i], acc[i][j]);
;     __builtin_amdgcn_s_setprio(0);
;   }
; }
; DI void g8_load1o(u32x4 (&r4)[4], const bf16_t* base, const unsigned (&off)[4]) {
; #pragma unroll
;   for (int i = 0; i < 4; ++i) r4[i] = *(const u32x4*)(base + off[i]);
; }
; DI void gemm8_accum(f32x4 (&acc)[8][4], const bf16_t* a, size_t lda, const bf16_t* b, size_t ldb, int nkb, bf16_t* L,
;                     const bool pre, const bf16_t* an, size_t ldan, const bf16_t* bn, size_t ldbn) {
;   const int tid = TID8(), lane = tid & 63, w = tid >> 6;
;   const int wm = w >> 2, wn = w & 3;
;   const int lrow = tid >> 3, lch = tid & 7;
;   u32x4 ra[4], rb[4];
;   unsigned offa[4], offb[4];
; #pragma unroll
;   for (int i = 0; i < 4; ++i) {
;     offa[i] = (unsigned)(lrow + 64 * i) * (unsigned)lda + (unsigned)(lch * 8);
;     offb[i] = (unsigned)(lrow + 64 * i) * (unsigned)ldb + (unsigned)(lch * 8);
;   }
;   if (!pre) {
;     g8_load1o(ra, a, offa);
;     g8_load1o(rb, b, offb);
;     __syncthreads();
;     g8_store(L, ra, rb, lrow, lch);
;   }
;   g8_load1o(ra, a + 64, offa);
;   g8_load1o(rb, b + 64, offb);
;   for (int kb = 0; kb + 2 < nkb; ++kb) {
;     __syncthreads();
;     g8_store1(L + ((kb + 1) & 1) * 32768, ra, lrow, lch);
;     g8_load1o(ra, a + (kb + 2) * 64, offa);
;     __builtin_amdgcn_sched_barrier(0);
;     g8_compute<0, 1>(acc, L + (kb & 1) * 32768, wm, wn, lane);
;     __builtin_amdgcn_sched_barrier(0);
;     g8_store1(L + ((kb + 1) & 1) * 32768 + 16384, rb, lrow, lch);
;     g8_load1o(rb, b + (kb + 2) * 64, offb);
;     __builtin_amdgcn_sched_barrier(0);
;     g8_compute<1, 2>(acc, L + (kb & 1) * 32768, wm, wn, lane);
;   }
.Lstg_942_a:
	s_waitcnt vmcnt(5)
	ds_write_b128 v167, v[22:25]
	ds_write_b128 v167, v[18:21] offset:8192
	ds_write_b128 v167, v[26:29] offset:16384
	s_waitcnt vmcnt(4)
	ds_write_b128 v167, v[30:33] offset:24576
	s_add_u32 s54, s52, s0
	s_addc_u32 s55, s53, s1
	global_load_dwordx4 v[22:25], v185, s[54:55]
	global_load_dwordx4 v[26:29], v181, s[54:55]
	global_load_dwordx4 v[18:21], v183, s[54:55]
	global_load_dwordx4 v[30:33], v179, s[54:55]
	s_and_b32 s2, s2, 0x8000
	s_lshl_b32 s2, s2, 1
	v_lshl_add_u32 v169, v191, 1, s2
	v_add_u32_e32 v222, v169, v187
	ds_read_b128 v[192:195], v222
	ds_read_b128 v[198:201], v222 offset:2048
	ds_read_b128 v[202:205], v222 offset:4096
	ds_read_b128 v[206:209], v222 offset:6144
	ds_read_b128 v[210:213], v222 offset:8192
	ds_read_b128 v[214:217], v222 offset:10240
	ds_read_b128 v[218:221], v222 offset:12288
	ds_read_b128 v[222:225], v222 offset:14336
	v_add_u32_e32 v169, v169, v186
	ds_read_b128 v[226:229], v169 offset:32768
	ds_read_b128 v[230:233], v169 offset:34816
	ds_read_b128 v[234:237], v169 offset:36864
	ds_read_b128 v[238:241], v169 offset:38912
	s_waitcnt lgkmcnt(3)
	v_mfma_f32_16x16x32_bf16 v[158:161], v[226:229], v[192:195], v[158:161]
	s_waitcnt lgkmcnt(2)
	v_mfma_f32_16x16x32_bf16 v[154:157], v[230:233], v[192:195], v[154:157]
	s_waitcnt lgkmcnt(1)
	v_mfma_f32_16x16x32_bf16 v[150:153], v[234:237], v[192:195], v[150:153]
	s_waitcnt lgkmcnt(0)
	v_mfma_f32_16x16x32_bf16 v[146:149], v[238:241], v[192:195], v[146:149]
	v_mfma_f32_16x16x32_bf16 v[142:145], v[226:229], v[198:201], v[142:145]
	v_mfma_f32_16x16x32_bf16 v[138:141], v[230:233], v[198:201], v[138:141]
	v_mfma_f32_16x16x32_bf16 v[134:137], v[234:237], v[198:201], v[134:137]
	v_mfma_f32_16x16x32_bf16 v[130:133], v[238:241], v[198:201], v[130:133]
	v_mfma_f32_16x16x32_bf16 v[126:129], v[226:229], v[202:205], v[126:129]
	v_mfma_f32_16x16x32_bf16 v[122:125], v[230:233], v[202:205], v[122:125]
	v_mfma_f32_16x16x32_bf16 v[118:121], v[234:237], v[202:205], v[118:121]
	v_mfma_f32_16x16x32_bf16 v[114:117], v[238:241], v[202:205], v[114:117]
	v_mfma_f32_16x16x32_bf16 v[110:113], v[226:229], v[206:209], v[110:113]
	v_mfma_f32_16x16x32_bf16 v[106:109], v[230:233], v[206:209], v[106:109]
	v_mfma_f32_16x16x32_bf16 v[102:105], v[234:237], v[206:209], v[102:105]
	v_mfma_f32_16x16x32_bf16 v[98:101], v[238:241], v[206:209], v[98:101]
	v_mfma_f32_16x16x32_bf16 v[94:97], v[226:229], v[210:213], v[94:97]
	v_mfma_f32_16x16x32_bf16 v[90:93], v[230:233], v[210:213], v[90:93]
	v_mfma_f32_16x16x32_bf16 v[86:89], v[234:237], v[210:213], v[86:89]
	v_mfma_f32_16x16x32_bf16 v[82:85], v[238:241], v[210:213], v[82:85]
	v_mfma_f32_16x16x32_bf16 v[78:81], v[226:229], v[214:217], v[78:81]
	v_mfma_f32_16x16x32_bf16 v[74:77], v[230:233], v[214:217], v[74:77]
	v_mfma_f32_16x16x32_bf16 v[70:73], v[234:237], v[214:217], v[70:73]
	v_mfma_f32_16x16x32_bf16 v[66:69], v[238:241], v[214:217], v[66:69]
	v_mfma_f32_16x16x32_bf16 v[62:65], v[226:229], v[218:221], v[62:65]
	v_mfma_f32_16x16x32_bf16 v[58:61], v[230:233], v[218:221], v[58:61]
	v_mfma_f32_16x16x32_bf16 v[54:57], v[234:237], v[218:221], v[54:57]
	v_mfma_f32_16x16x32_bf16 v[50:53], v[238:241], v[218:221], v[50:53]
	v_mfma_f32_16x16x32_bf16 v[46:49], v[226:229], v[222:225], v[46:49]
	v_mfma_f32_16x16x32_bf16 v[42:45], v[230:233], v[222:225], v[42:45]
	v_mfma_f32_16x16x32_bf16 v[38:41], v[234:237], v[222:225], v[38:41]
	v_mfma_f32_16x16x32_bf16 v[34:37], v[238:241], v[222:225], v[34:37]
	s_waitcnt vmcnt(7)
	ds_write_b128 v167, v[14:17] offset:32768
	s_waitcnt vmcnt(6)
	ds_write_b128 v167, v[2:5] offset:40960
	s_waitcnt vmcnt(5)
	ds_write_b128 v167, v[6:9] offset:49152
	s_waitcnt vmcnt(4)
	ds_write_b128 v167, v[10:13] offset:57344
	s_add_u32 s58, s56, s0
	s_addc_u32 s59, s57, s1
	global_load_dwordx4 v[14:17], v177, s[58:59]
	global_load_dwordx4 v[2:5], v175, s[58:59]
	global_load_dwordx4 v[6:9], v173, s[58:59]
	global_load_dwordx4 v[10:13], v171, s[58:59]
	v_lshl_add_u32 v167, v188, 1, s2
	v_add_u32_e32 v169, v167, v187
	ds_read_b128 v[192:195], v169
	ds_read_b128 v[198:201], v169 offset:2048
	ds_read_b128 v[202:205], v169 offset:4096
	ds_read_b128 v[206:209], v169 offset:6144
	ds_read_b128 v[210:213], v169 offset:8192
	ds_read_b128 v[214:217], v169 offset:10240
	ds_read_b128 v[218:221], v169 offset:12288
	ds_read_b128 v[222:225], v169 offset:14336
	v_add_u32_e32 v167, v167, v186
	ds_read_b128 v[226:229], v167 offset:32768
	ds_read_b128 v[230:233], v167 offset:34816
	ds_read_b128 v[234:237], v167 offset:36864
	ds_read_b128 v[238:241], v167 offset:38912
	s_cmp_lg_u32 s101, 0
	s_cbranch_scc1 .Lstg_942_b
	s_waitcnt lgkmcnt(3)
	v_mfma_f32_16x16x32_bf16 v[158:161], v[226:229], v[192:195], v[158:161]
	s_waitcnt lgkmcnt(2)
	v_mfma_f32_16x16x32_bf16 v[154:157], v[230:233], v[192:195], v[154:157]
	s_waitcnt lgkmcnt(1)
	v_mfma_f32_16x16x32_bf16 v[150:153], v[234:237], v[192:195], v[150:153]
	s_waitcnt lgkmcnt(0)
	v_mfma_f32_16x16x32_bf16 v[146:149], v[238:241], v[192:195], v[146:149]
	v_mfma_f32_16x16x32_bf16 v[142:145], v[226:229], v[198:201], v[142:145]
	v_mfma_f32_16x16x32_bf16 v[138:141], v[230:233], v[198:201], v[138:141]
	v_mfma_f32_16x16x32_bf16 v[134:137], v[234:237], v[198:201], v[134:137]
	v_mfma_f32_16x16x32_bf16 v[130:133], v[238:241], v[198:201], v[130:133]
	v_mfma_f32_16x16x32_bf16 v[126:129], v[226:229], v[202:205], v[126:129]
	v_mfma_f32_16x16x32_bf16 v[122:125], v[230:233], v[202:205], v[122:125]
	v_mfma_f32_16x16x32_bf16 v[118:121], v[234:237], v[202:205], v[118:121]
	v_mfma_f32_16x16x32_bf16 v[114:117], v[238:241], v[202:205], v[114:117]
	v_mfma_f32_16x16x32_bf16 v[110:113], v[226:229], v[206:209], v[110:113]
	v_mfma_f32_16x16x32_bf16 v[106:109], v[230:233], v[206:209], v[106:109]
	v_mfma_f32_16x16x32_bf16 v[102:105], v[234:237], v[206:209], v[102:105]
	v_mfma_f32_16x16x32_bf16 v[98:101], v[238:241], v[206:209], v[98:101]
	v_mfma_f32_16x16x32_bf16 v[94:97], v[226:229], v[210:213], v[94:97]
	v_mfma_f32_16x16x32_bf16 v[90:93], v[230:233], v[210:213], v[90:93]
	v_mfma_f32_16x16x32_bf16 v[86:89], v[234:237], v[210:213], v[86:89]
	v_mfma_f32_16x16x32_bf16 v[82:85], v[238:241], v[210:213], v[82:85]
	v_mfma_f32_16x16x32_bf16 v[78:81], v[226:229], v[214:217], v[78:81]
	v_mfma_f32_16x16x32_bf16 v[74:77], v[230:233], v[214:217], v[74:77]
	v_mfma_f32_16x16x32_bf16 v[70:73], v[234:237], v[214:217], v[70:73]
	v_mfma_f32_16x16x32_bf16 v[66:69], v[238:241], v[214:217], v[66:69]
	v_mfma_f32_16x16x32_bf16 v[62:65], v[226:229], v[218:221], v[62:65]
	v_mfma_f32_16x16x32_bf16 v[58:61], v[230:233], v[218:221], v[58:61]
	v_mfma_f32_16x16x32_bf16 v[54:57], v[234:237], v[218:221], v[54:57]
	v_mfma_f32_16x16x32_bf16 v[50:53], v[238:241], v[218:221], v[50:53]
	v_mfma_f32_16x16x32_bf16 v[46:49], v[226:229], v[222:225], v[46:49]
	v_mfma_f32_16x16x32_bf16 v[42:45], v[230:233], v[222:225], v[42:45]
	v_mfma_f32_16x16x32_bf16 v[38:41], v[234:237], v[222:225], v[38:41]
	v_mfma_f32_16x16x32_bf16 v[34:37], v[238:241], v[222:225], v[34:37]

; #pragma unroll
;   for (int ks = KS0; ks < KS1; ++ks) {
;     bf16x8 af[8], bfr[4];
; #pragma unroll
;     for (int i = 0; i < 8; ++i) {
;       const int r = wm * 128 + i * 16 + (lane & 15);
;       af[i] = *(const bf16x8*)(S + r * 64 + (((ks * 4 + (lane >> 4)) ^ ((r >> 1) & 7)) << 3));
;     }
; #pragma unroll
;     for (int j = 0; j < 4; ++j) {
;       const int r = wn * 64 + j * 16 + (lane & 15);
;       bfr[j] = *(const bf16x8*)(S + 16384 + r * 64 + (((ks * 4 + (lane >> 4)) ^ ((r >> 1) & 7)) << 3));
;     }
;     __builtin_amdgcn_s_setprio(1);
; #pragma unroll
;     for (int i = 0; i < 8; ++i)
; #pragma unroll
;       for (int j = 0; j < 4; ++j) acc[i][j] = mfma16(bfr[j], af[i], acc[i][j]);
;     __builtin_amdgcn_s_setprio(0);
;   }
; }
; DI void g8_load1o(u32x4 (&r4)[4], const bf16_t* base, const unsigned (&off)[4]) {
; #pragma unroll
;   for (int i = 0; i < 4; ++i) r4[i] = *(const u32x4*)(base + off[i]);
; }
; DI void gemm8_accum(f32x4 (&acc)[8][4], const bf16_t* a, size_t lda, const bf16_t* b, size_t ldb, int nkb, bf16_t* L,
;                     const bool pre, const bf16_t* an, size_t ldan, const bf16_t* bn, size_t ldbn) {
;   const int tid = TID8(), lane = tid & 63, w = tid >> 6;
;   const int wm = w >> 2, wn = w & 3;
;   const int lrow = tid >> 3, lch = tid & 7;
;   u32x4 ra[4], rb[4];
;   unsigned offa[4], offb[4];
; #pragma unroll
;   for (int i = 0; i < 4; ++i) {
;     offa[i] = (unsigned)(lrow + 64 * i) * (unsigned)lda + (unsigned)(lch * 8);
;     offb[i] = (unsigned)(lrow + 64 * i) * (unsigned)ldb + (unsigned)(lch * 8);
;   }
;   if (!pre) {
;     g8_load1o(ra, a, offa);
;     g8_load1o(rb, b, offb);
;     __syncthreads();
;     g8_store(L, ra, rb, lrow, lch);
;   }
;   g8_load1o(ra, a + 64, offa);
;   g8_load1o(rb, b + 64, offb);
;   for (int kb = 0; kb + 2 < nkb; ++kb) {
;     __syncthreads();
;     g8_store1(L + ((kb + 1) & 1) * 32768, ra, lrow, lch);
;     g8_load1o(ra, a + (kb + 2) * 64, offa);
;     __builtin_amdgcn_sched_barrier(0);
;     g8_compute<0, 1>(acc, L + (kb & 1) * 32768, wm, wn, lane);
;     __builtin_amdgcn_sched_barrier(0);
;     g8_store1(L + ((kb + 1) & 1) * 32768 + 16384, rb, lrow, lch);
;     g8_load1o(rb, b + (kb + 2) * 64, offb);
;     __builtin_amdgcn_sched_barrier(0);
;     g8_compute<1, 2>(acc, L + (kb & 1) * 32768, wm, wn, lane);
;   }
.Lstg_1007_a:
	s_waitcnt vmcnt(7)
	ds_write_b128 v0, v[34:37]
	s_waitcnt vmcnt(6)
	ds_write_b128 v0, v[42:45] offset:8192
	s_waitcnt vmcnt(5)
	ds_write_b128 v0, v[54:57] offset:16384
	s_waitcnt vmcnt(4)
	ds_write_b128 v0, v[94:97] offset:24576
	s_add_u32 s54, s52, s0
	s_addc_u32 s55, s53, s1
	global_load_dwordx4 v[34:37], v179, s[54:55]
	global_load_dwordx4 v[42:45], v177, s[54:55]
	global_load_dwordx4 v[54:57], v175, s[54:55]
	global_load_dwordx4 v[94:97], v173, s[54:55]
	s_and_b32 s2, s2, 0x8000
	s_lshl_b32 s2, s2, 1
	v_lshl_add_u32 v191, v186, 1, s2
	v_add_u32_e32 v222, v191, v181
	ds_read_b128 v[192:195], v222
	ds_read_b128 v[198:201], v222 offset:2048
	ds_read_b128 v[202:205], v222 offset:4096
	ds_read_b128 v[206:209], v222 offset:6144
	ds_read_b128 v[210:213], v222 offset:8192
	ds_read_b128 v[214:217], v222 offset:10240
	ds_read_b128 v[218:221], v222 offset:12288
	ds_read_b128 v[222:225], v222 offset:14336
	v_add_u32_e32 v191, v191, v180
	ds_read_b128 v[226:229], v191 offset:32768
	ds_read_b128 v[230:233], v191 offset:34816
	ds_read_b128 v[234:237], v191 offset:36864
	ds_read_b128 v[238:241], v191 offset:38912
	s_waitcnt lgkmcnt(3)
	v_mfma_f32_16x16x32_bf16 v[158:161], v[226:229], v[192:195], v[158:161]
	s_waitcnt lgkmcnt(2)
	v_mfma_f32_16x16x32_bf16 v[154:157], v[230:233], v[192:195], v[154:157]
	s_waitcnt lgkmcnt(1)
	v_mfma_f32_16x16x32_bf16 v[150:153], v[234:237], v[192:195], v[150:153]
	s_waitcnt lgkmcnt(0)
	v_mfma_f32_16x16x32_bf16 v[146:149], v[238:241], v[192:195], v[146:149]
	v_mfma_f32_16x16x32_bf16 v[142:145], v[226:229], v[198:201], v[142:145]
	v_mfma_f32_16x16x32_bf16 v[138:141], v[230:233], v[198:201], v[138:141]
	v_mfma_f32_16x16x32_bf16 v[134:137], v[234:237], v[198:201], v[134:137]
	v_mfma_f32_16x16x32_bf16 v[130:133], v[238:241], v[198:201], v[130:133]
	v_mfma_f32_16x16x32_bf16 v[126:129], v[226:229], v[202:205], v[126:129]
	v_mfma_f32_16x16x32_bf16 v[122:125], v[230:233], v[202:205], v[122:125]
	v_mfma_f32_16x16x32_bf16 v[118:121], v[234:237], v[202:205], v[118:121]
	v_mfma_f32_16x16x32_bf16 v[114:117], v[238:241], v[202:205], v[114:117]
	v_mfma_f32_16x16x32_bf16 v[110:113], v[226:229], v[206:209], v[110:113]
	v_mfma_f32_16x16x32_bf16 v[106:109], v[230:233], v[206:209], v[106:109]
	v_mfma_f32_16x16x32_bf16 v[102:105], v[234:237], v[206:209], v[102:105]
	v_mfma_f32_16x16x32_bf16 v[98:101], v[238:241], v[206:209], v[98:101]
	v_mfma_f32_16x16x32_bf16 v[90:93], v[226:229], v[210:213], v[90:93]
	v_mfma_f32_16x16x32_bf16 v[86:89], v[230:233], v[210:213], v[86:89]
	v_mfma_f32_16x16x32_bf16 v[82:85], v[234:237], v[210:213], v[82:85]
	v_mfma_f32_16x16x32_bf16 v[78:81], v[238:241], v[210:213], v[78:81]
	v_mfma_f32_16x16x32_bf16 v[74:77], v[226:229], v[214:217], v[74:77]
	v_mfma_f32_16x16x32_bf16 v[70:73], v[230:233], v[214:217], v[70:73]
	v_mfma_f32_16x16x32_bf16 v[66:69], v[234:237], v[214:217], v[66:69]
	v_mfma_f32_16x16x32_bf16 v[62:65], v[238:241], v[214:217], v[62:65]
	v_mfma_f32_16x16x32_bf16 v[58:61], v[226:229], v[218:221], v[58:61]
	v_mfma_f32_16x16x32_bf16 v[50:53], v[230:233], v[218:221], v[50:53]
	v_mfma_f32_16x16x32_bf16 v[46:49], v[234:237], v[218:221], v[46:49]
	v_mfma_f32_16x16x32_bf16 v[38:41], v[238:241], v[218:221], v[38:41]
	v_mfma_f32_16x16x32_bf16 v[30:33], v[226:229], v[222:225], v[30:33]
	v_mfma_f32_16x16x32_bf16 v[26:29], v[230:233], v[222:225], v[26:29]
	v_mfma_f32_16x16x32_bf16 v[22:25], v[234:237], v[222:225], v[22:25]
	v_mfma_f32_16x16x32_bf16 v[18:21], v[238:241], v[222:225], v[18:21]
	s_waitcnt vmcnt(7)
	ds_write_b128 v0, v[14:17] offset:32768
	s_waitcnt vmcnt(6)
	ds_write_b128 v0, v[2:5] offset:40960
	s_waitcnt vmcnt(5)
	ds_write_b128 v0, v[6:9] offset:49152
	s_waitcnt vmcnt(4)
	ds_write_b128 v0, v[10:13] offset:57344
	s_add_u32 s58, s56, s0
	s_addc_u32 s59, s57, s1
	global_load_dwordx4 v[14:17], v171, s[58:59]
	global_load_dwordx4 v[2:5], v169, s[58:59]
	global_load_dwordx4 v[6:9], v167, s[58:59]
	global_load_dwordx4 v[10:13], v165, s[58:59]
	v_lshl_add_u32 v0, v182, 1, s2
	v_add_u32_e32 v191, v0, v181
	ds_read_b128 v[192:195], v191
	ds_read_b128 v[198:201], v191 offset:2048
	ds_read_b128 v[202:205], v191 offset:4096
	ds_read_b128 v[206:209], v191 offset:6144
	ds_read_b128 v[210:213], v191 offset:8192
	ds_read_b128 v[214:217], v191 offset:10240
	ds_read_b128 v[218:221], v191 offset:12288
	ds_read_b128 v[222:225], v191 offset:14336
	v_add_u32_e32 v0, v0, v180
	ds_read_b128 v[226:229], v0 offset:32768
	ds_read_b128 v[230:233], v0 offset:34816
	ds_read_b128 v[234:237], v0 offset:36864
	ds_read_b128 v[238:241], v0 offset:38912
	s_cmp_lg_u32 s101, 0
	s_cbranch_scc1 .Lstg_1007_b
	s_waitcnt lgkmcnt(3)
	v_mfma_f32_16x16x32_bf16 v[158:161], v[226:229], v[192:195], v[158:161]
	s_waitcnt lgkmcnt(2)
	v_mfma_f32_16x16x32_bf16 v[154:157], v[230:233], v[192:195], v[154:157]
	s_waitcnt lgkmcnt(1)
	v_mfma_f32_16x16x32_bf16 v[150:153], v[234:237], v[192:195], v[150:153]
	s_waitcnt lgkmcnt(0)
	v_mfma_f32_16x16x32_bf16 v[146:149], v[238:241], v[192:195], v[146:149]
	v_mfma_f32_16x16x32_bf16 v[142:145], v[226:229], v[198:201], v[142:145]
	v_mfma_f32_16x16x32_bf16 v[138:141], v[230:233], v[198:201], v[138:141]
	v_mfma_f32_16x16x32_bf16 v[134:137], v[234:237], v[198:201], v[134:137]
	v_mfma_f32_16x16x32_bf16 v[130:133], v[238:241], v[198:201], v[130:133]
	v_mfma_f32_16x16x32_bf16 v[126:129], v[226:229], v[202:205], v[126:129]
	v_mfma_f32_16x16x32_bf16 v[122:125], v[230:233], v[202:205], v[122:125]
	v_mfma_f32_16x16x32_bf16 v[118:121], v[234:237], v[202:205], v[118:121]
	v_mfma_f32_16x16x32_bf16 v[114:117], v[238:241], v[202:205], v[114:117]
	v_mfma_f32_16x16x32_bf16 v[110:113], v[226:229], v[206:209], v[110:113]
	v_mfma_f32_16x16x32_bf16 v[106:109], v[230:233], v[206:209], v[106:109]
	v_mfma_f32_16x16x32_bf16 v[102:105], v[234:237], v[206:209], v[102:105]
	v_mfma_f32_16x16x32_bf16 v[98:101], v[238:241], v[206:209], v[98:101]
	v_mfma_f32_16x16x32_bf16 v[90:93], v[226:229], v[210:213], v[90:93]
	v_mfma_f32_16x16x32_bf16 v[86:89], v[230:233], v[210:213], v[86:89]
	v_mfma_f32_16x16x32_bf16 v[82:85], v[234:237], v[210:213], v[82:85]
	v_mfma_f32_16x16x32_bf16 v[78:81], v[238:241], v[210:213], v[78:81]
	v_mfma_f32_16x16x32_bf16 v[74:77], v[226:229], v[214:217], v[74:77]
	v_mfma_f32_16x16x32_bf16 v[70:73], v[230:233], v[214:217], v[70:73]
	v_mfma_f32_16x16x32_bf16 v[66:69], v[234:237], v[214:217], v[66:69]
	v_mfma_f32_16x16x32_bf16 v[62:65], v[238:241], v[214:217], v[62:65]
	v_mfma_f32_16x16x32_bf16 v[58:61], v[226:229], v[218:221], v[58:61]
	v_mfma_f32_16x16x32_bf16 v[50:53], v[230:233], v[218:221], v[50:53]
	v_mfma_f32_16x16x32_bf16 v[46:49], v[234:237], v[218:221], v[46:49]
	v_mfma_f32_16x16x32_bf16 v[38:41], v[238:241], v[218:221], v[38:41]
	v_mfma_f32_16x16x32_bf16 v[30:33], v[226:229], v[222:225], v[30:33]
	v_mfma_f32_16x16x32_bf16 v[26:29], v[230:233], v[222:225], v[26:29]
	v_mfma_f32_16x16x32_bf16 v[22:25], v[234:237], v[222:225], v[22:25]
	v_mfma_f32_16x16x32_bf16 v[18:21], v[238:241], v[222:225], v[18:21]
